# v15 plus: saddr-form LDS-DMA (no VALU address adds) also in the w_in, down and w_out K-loops
# speedup vs baseline: 1.0216x; 1.0051x over previous
; #define PG8_STAGE(bufoff, gbase, voff) do { _Pragma("unroll") for (int _i = 0; _i < 2; ++_i) \
;         __builtin_amdgcn_global_load_lds((const unsigned*)((const char*)(gbase) + (voff)[_i]), (LAS unsigned*)(lds + (bufoff) + ldsw + _i * 8192), 16, 0, 0); } while (0)
; #define PG8_LDA(dst, b, h) do { _Pragma("unroll") for (int m = 0; m < 4; ++m) _Pragma("unroll") for (int k = 0; k < 2; ++k) dst[m][k] = *(const LAS bf16x8*)(lds + PG8_SA(b, h) + aoff + m * 2048 + k * 1024); } while (0)
; #define PG8_LDB(dst, b, h) do { _Pragma("unroll") for (int n = 0; n < 2; ++n) _Pragma("unroll") for (int k = 0; k < 2; ++k) dst[n][k] = *(const LAS bf16x8*)(lds + PG8_SB(b, h) + boff + n * 2048 + k * 1024); } while (0)
; #define PG8_MMA(ai, bj, At, Bt) do { __builtin_amdgcn_s_setprio(1); _Pragma("unroll") for (int m = 0; m < 4; ++m) _Pragma("unroll") for (int n = 0; n < 2; ++n) _Pragma("unroll") for (int k = 0; k < 2; ++k) \
;         acc[ai][bj][m][n] = __builtin_amdgcn_mfma_f32_16x16x32_bf16(Bt[n][k], At[m][k], acc[ai][bj][m][n], 0, 0, 0); __builtin_amdgcn_s_setprio(0); } while (0)
; #define PG8_WAIT_V(n) asm volatile("s_waitcnt vmcnt(" #n ")" ::: "memory")
; #define PG8_WAIT_L(n) asm volatile("s_waitcnt lgkmcnt(" #n ")" ::: "memory")
; #define PG8_BAR __builtin_amdgcn_s_barrier()
; #define PG8_SCHED __builtin_amdgcn_sched_barrier(0)
; template <class Epi, class Sched>
; __device__ __forceinline__ void gemm_phase(LAS unsigned char* lds, const Gemm g, const Sched& S, const Epi& E) {
;     ...
;             PG8_LDB(B0, 0, 0); PG8_SCHED; PG8_LDA(At, 0, 0); PG8_STAGE(PG8_SA(1, 1), a1 + hstep, voffA);
;             PG8_WAIT_L(8); PG8_BAR; PG8_WAIT_L(0); PG8_MMA(0, 0, At, B0); PG8_BAR; PG8_SCHED;
;             PG8_LDB(B1, 0, 1); PG8_STAGE(PG8_SB(0, 0), b2, voffB);
;             PG8_BAR; PG8_WAIT_L(0); PG8_MMA(0, 1, At, B1); PG8_BAR;
;             PG8_LDA(At, 0, 1); PG8_STAGE(PG8_SA(0, 0), a2, voffA);
;             PG8_BAR; PG8_WAIT_L(0); PG8_MMA(1, 0, At, B0); PG8_BAR; PG8_SCHED;
;             PG8_STAGE(PG8_SB(0, 1), b2 + hstep, voffB);
;             PG8_WAIT_V(6); PG8_BAR; PG8_MMA(1, 1, At, B1); PG8_BAR;
.LBB0_125:
	s_add_u32 s20, s16, 0xfff80080
	s_addc_u32 s21, s17, -1
	s_add_i32 s45, 0, 0x10000
	v_add_u32_e32 v146, s45, v143
	ds_read_b128 v[138:141], v146
	ds_read_b128 v[160:163], v146 offset:1024
	ds_read_b128 v[164:167], v146 offset:2048
	ds_read_b128 v[168:171], v146 offset:3072
	s_cmp_eq_u32 s44, 28
	s_cselect_b32 s23, s7, s21
	s_cselect_b32 s22, s40, s20
	s_cselect_b32 s21, s5, s43
	s_cselect_b32 s20, s41, s42
	s_add_i32 m0, s30, 0xc000
	ds_read_b128 v[172:175], v145
	ds_read_b128 v[200:203], v145 offset:1024
	ds_read_b128 v[204:207], v145 offset:2048
	ds_read_b128 v[208:211], v145 offset:3072
	ds_read_b128 v[212:215], v145 offset:4096
	ds_read_b128 v[216:219], v145 offset:5120
	ds_read_b128 v[220:223], v145 offset:6144
	ds_read_b128 v[224:227], v145 offset:7168
	global_load_lds_dwordx4 v134, s[16:17]
	s_add_i32 m0, s30, 0xe000
	s_nop 0
	global_load_lds_dwordx4 v136, s[16:17]
	s_waitcnt lgkmcnt(8)
	s_barrier
	s_waitcnt lgkmcnt(0)
	s_waitcnt lgkmcnt(0)
	v_mfma_f32_16x16x32_bf16 v[124:127], v[138:141], v[172:175], v[124:127]
	v_mfma_f32_16x16x32_bf16 v[120:123], v[164:167], v[172:175], v[120:123]
	v_mfma_f32_16x16x32_bf16 v[116:119], v[138:141], v[204:207], v[116:119]
	v_mfma_f32_16x16x32_bf16 v[108:111], v[164:167], v[204:207], v[108:111]
	v_mfma_f32_16x16x32_bf16 v[100:103], v[138:141], v[212:215], v[100:103]
	v_mfma_f32_16x16x32_bf16 v[92:95], v[164:167], v[212:215], v[92:95]
	v_mfma_f32_16x16x32_bf16 v[84:87], v[138:141], v[220:223], v[84:87]
	v_mfma_f32_16x16x32_bf16 v[76:79], v[164:167], v[220:223], v[76:79]
	v_mfma_f32_16x16x32_bf16 v[124:127], v[160:163], v[200:203], v[124:127]
	v_mfma_f32_16x16x32_bf16 v[120:123], v[168:171], v[200:203], v[120:123]
	v_mfma_f32_16x16x32_bf16 v[116:119], v[160:163], v[208:211], v[116:119]
	v_mfma_f32_16x16x32_bf16 v[108:111], v[168:171], v[208:211], v[108:111]
	v_mfma_f32_16x16x32_bf16 v[100:103], v[160:163], v[216:219], v[100:103]
	v_mfma_f32_16x16x32_bf16 v[92:95], v[168:171], v[216:219], v[92:95]
	v_mfma_f32_16x16x32_bf16 v[84:87], v[160:163], v[224:227], v[84:87]
	v_mfma_f32_16x16x32_bf16 v[76:79], v[168:171], v[224:227], v[76:79]
	s_barrier
	s_add_i32 s48, 0, 0x14000
	v_add_u32_e32 v146, s48, v143
	s_add_i32 s45, s45, s29
	ds_read_b128 v[228:231], v146
	ds_read_b128 v[232:235], v146 offset:1024
	ds_read_b128 v[236:239], v146 offset:2048
	ds_read_b128 v[240:243], v146 offset:3072
	s_add_u32 s84, s20, 0x80
	s_addc_u32 s85, s21, 0
	s_mov_b32 m0, s45
	s_nop 0
	global_load_lds_dwordx4 v148, s[20:21]
	s_add_i32 m0, s45, 0x2000
	s_nop 0
	global_load_lds_dwordx4 v128, s[20:21]
	s_barrier
	s_waitcnt lgkmcnt(0)
	s_waitcnt lgkmcnt(0)
	v_mfma_f32_16x16x32_bf16 v[112:115], v[228:231], v[172:175], v[112:115]
	v_mfma_f32_16x16x32_bf16 v[104:107], v[236:239], v[172:175], v[104:107]
	v_mfma_f32_16x16x32_bf16 v[96:99], v[228:231], v[204:207], v[96:99]
	v_mfma_f32_16x16x32_bf16 v[88:91], v[236:239], v[204:207], v[88:91]
	v_mfma_f32_16x16x32_bf16 v[80:83], v[228:231], v[212:215], v[80:83]
	v_mfma_f32_16x16x32_bf16 v[72:75], v[236:239], v[212:215], v[72:75]
	v_mfma_f32_16x16x32_bf16 v[68:71], v[228:231], v[220:223], v[68:71]
	v_mfma_f32_16x16x32_bf16 v[64:67], v[236:239], v[220:223], v[64:67]
	v_mfma_f32_16x16x32_bf16 v[112:115], v[232:235], v[200:203], v[112:115]
	v_mfma_f32_16x16x32_bf16 v[104:107], v[240:243], v[200:203], v[104:107]
	v_mfma_f32_16x16x32_bf16 v[96:99], v[232:235], v[208:211], v[96:99]
	v_mfma_f32_16x16x32_bf16 v[88:91], v[240:243], v[208:211], v[88:91]
	v_mfma_f32_16x16x32_bf16 v[80:83], v[232:235], v[216:219], v[80:83]
	v_mfma_f32_16x16x32_bf16 v[72:75], v[240:243], v[216:219], v[72:75]
	v_mfma_f32_16x16x32_bf16 v[68:71], v[232:235], v[224:227], v[68:71]
	v_mfma_f32_16x16x32_bf16 v[64:67], v[240:243], v[224:227], v[64:67]
	s_mov_b32 m0, s30
	s_add_u32 s86, s22, 0x80
	s_addc_u32 s87, s23, 0
	s_barrier
	ds_read_b128 v[172:175], v145 offset:16384
	ds_read_b128 v[200:203], v145 offset:17408
	ds_read_b128 v[204:207], v145 offset:18432
	ds_read_b128 v[208:211], v145 offset:19456
	ds_read_b128 v[212:215], v145 offset:20480
	ds_read_b128 v[216:219], v145 offset:21504
	ds_read_b128 v[220:223], v145 offset:22528
	ds_read_b128 v[224:227], v145 offset:23552
	global_load_lds_dwordx4 v132, s[22:23]
	s_mov_b32 m0, s31
	s_nop 0
	global_load_lds_dwordx4 v130, s[22:23]
	s_barrier
	s_waitcnt lgkmcnt(0)
	s_waitcnt lgkmcnt(0)
	v_mfma_f32_16x16x32_bf16 v[60:63], v[138:141], v[172:175], v[60:63]
	v_mfma_f32_16x16x32_bf16 v[56:59], v[164:167], v[172:175], v[56:59]
	v_mfma_f32_16x16x32_bf16 v[52:55], v[138:141], v[204:207], v[52:55]
	v_mfma_f32_16x16x32_bf16 v[44:47], v[164:167], v[204:207], v[44:47]
	v_mfma_f32_16x16x32_bf16 v[36:39], v[138:141], v[212:215], v[36:39]
	v_mfma_f32_16x16x32_bf16 v[28:31], v[164:167], v[212:215], v[28:31]
	v_mfma_f32_16x16x32_bf16 v[20:23], v[138:141], v[220:223], v[20:23]
	v_mfma_f32_16x16x32_bf16 v[12:15], v[164:167], v[220:223], v[12:15]
	v_mfma_f32_16x16x32_bf16 v[60:63], v[160:163], v[200:203], v[60:63]
	v_mfma_f32_16x16x32_bf16 v[56:59], v[168:171], v[200:203], v[56:59]
	v_mfma_f32_16x16x32_bf16 v[52:55], v[160:163], v[208:211], v[52:55]
	v_mfma_f32_16x16x32_bf16 v[44:47], v[168:171], v[208:211], v[44:47]
	v_mfma_f32_16x16x32_bf16 v[36:39], v[160:163], v[216:219], v[36:39]
	v_mfma_f32_16x16x32_bf16 v[28:31], v[168:171], v[216:219], v[28:31]
	v_mfma_f32_16x16x32_bf16 v[20:23], v[160:163], v[224:227], v[20:23]
	v_mfma_f32_16x16x32_bf16 v[12:15], v[168:171], v[224:227], v[12:15]
	s_barrier
	s_add_u32 s46, s20, 0x80000
	s_addc_u32 s47, s21, 0
	s_add_i32 s45, s48, s29
	s_mov_b32 m0, s45
	s_nop 0
	global_load_lds_dwordx4 v148, s[46:47]
	s_add_i32 m0, s45, 0x2000
	s_nop 0
	global_load_lds_dwordx4 v128, s[46:47]
	s_waitcnt vmcnt(6)
	s_barrier
; #define PG8_STAGE(bufoff, gbase, voff) do { _Pragma("unroll") for (int _i = 0; _i < 2; ++_i) \
;         __builtin_amdgcn_global_load_lds((const unsigned*)((const char*)(gbase) + (voff)[_i]), (LAS unsigned*)(lds + (bufoff) + ldsw + _i * 8192), 16, 0, 0); } while (0)
; #define PG8_LDA(dst, b, h) do { _Pragma("unroll") for (int m = 0; m < 4; ++m) _Pragma("unroll") for (int k = 0; k < 2; ++k) dst[m][k] = *(const LAS bf16x8*)(lds + PG8_SA(b, h) + aoff + m * 2048 + k * 1024); } while (0)
; #define PG8_LDB(dst, b, h) do { _Pragma("unroll") for (int n = 0; n < 2; ++n) _Pragma("unroll") for (int k = 0; k < 2; ++k) dst[n][k] = *(const LAS bf16x8*)(lds + PG8_SB(b, h) + boff + n * 2048 + k * 1024); } while (0)
; #define PG8_MMA(ai, bj, At, Bt) do { __builtin_amdgcn_s_setprio(1); _Pragma("unroll") for (int m = 0; m < 4; ++m) _Pragma("unroll") for (int n = 0; n < 2; ++n) _Pragma("unroll") for (int k = 0; k < 2; ++k) \
;         acc[ai][bj][m][n] = __builtin_amdgcn_mfma_f32_16x16x32_bf16(Bt[n][k], At[m][k], acc[ai][bj][m][n], 0, 0, 0); __builtin_amdgcn_s_setprio(0); } while (0)
; #define PG8_WAIT_V(n) asm volatile("s_waitcnt vmcnt(" #n ")" ::: "memory")
; #define PG8_WAIT_L(n) asm volatile("s_waitcnt lgkmcnt(" #n ")" ::: "memory")
; #define PG8_BAR __builtin_amdgcn_s_barrier()
; #define PG8_SCHED __builtin_amdgcn_sched_barrier(0)
; template <class Epi, class Sched>
; __device__ __forceinline__ void gemm_phase(LAS unsigned char* lds, const Gemm g, const Sched& S, const Epi& E) {
;     ...
;             PG8_WAIT_V(6); PG8_BAR; PG8_MMA(1, 1, At, B1); PG8_BAR;
;             PG8_LDB(B0, 1, 0); PG8_SCHED; PG8_LDA(At, 1, 0); PG8_STAGE(PG8_SA(0, 1), a2 + hstep, voffA);
;             PG8_WAIT_L(8); PG8_BAR; PG8_WAIT_L(0); PG8_MMA(0, 0, At, B0); PG8_BAR; PG8_SCHED;
;             PG8_LDB(B1, 1, 1); PG8_STAGE(PG8_SB(1, 0), b3, voffB);
;             PG8_BAR; PG8_WAIT_L(0); PG8_MMA(0, 1, At, B1); PG8_BAR;
;             PG8_LDA(At, 1, 1); PG8_STAGE(PG8_SA(1, 0), a3, voffA);
;             PG8_BAR; PG8_WAIT_L(0); PG8_MMA(1, 0, At, B0); PG8_BAR; PG8_SCHED;
	v_mfma_f32_16x16x32_bf16 v[48:51], v[228:231], v[172:175], v[48:51]
	v_mfma_f32_16x16x32_bf16 v[40:43], v[236:239], v[172:175], v[40:43]
	v_mfma_f32_16x16x32_bf16 v[32:35], v[228:231], v[204:207], v[32:35]
	v_mfma_f32_16x16x32_bf16 v[24:27], v[236:239], v[204:207], v[24:27]
	v_mfma_f32_16x16x32_bf16 v[16:19], v[228:231], v[212:215], v[16:19]
	v_mfma_f32_16x16x32_bf16 v[8:11], v[236:239], v[212:215], v[8:11]
	v_mfma_f32_16x16x32_bf16 v[4:7], v[228:231], v[220:223], v[4:7]
	v_mfma_f32_16x16x32_bf16 v[0:3], v[236:239], v[220:223], v[0:3]
	v_mfma_f32_16x16x32_bf16 v[48:51], v[232:235], v[200:203], v[48:51]
	v_mfma_f32_16x16x32_bf16 v[40:43], v[240:243], v[200:203], v[40:43]
	v_mfma_f32_16x16x32_bf16 v[32:35], v[232:235], v[208:211], v[32:35]
	v_mfma_f32_16x16x32_bf16 v[24:27], v[240:243], v[208:211], v[24:27]
	v_mfma_f32_16x16x32_bf16 v[16:19], v[232:235], v[216:219], v[16:19]
	v_mfma_f32_16x16x32_bf16 v[8:11], v[240:243], v[216:219], v[8:11]
	v_mfma_f32_16x16x32_bf16 v[4:7], v[232:235], v[224:227], v[4:7]
	v_mfma_f32_16x16x32_bf16 v[0:3], v[240:243], v[224:227], v[0:3]
	s_add_i32 s45, 0, 0x18000
	v_add_u32_e32 v168, s45, v143
	s_barrier
	ds_read_b128 v[138:141], v168
	ds_read_b128 v[160:163], v168 offset:1024
	ds_read_b128 v[164:167], v168 offset:2048
	ds_read_b128 v[168:171], v168 offset:3072
	s_add_u32 s22, s22, 0x80000
	s_addc_u32 s23, s23, 0
	s_mov_b32 m0, s33
	ds_read_b128 v[172:175], v145 offset:32768
	ds_read_b128 v[200:203], v145 offset:33792
	ds_read_b128 v[204:207], v145 offset:34816
	ds_read_b128 v[208:211], v145 offset:35840
	ds_read_b128 v[212:215], v145 offset:36864
	ds_read_b128 v[216:219], v145 offset:37888
	ds_read_b128 v[220:223], v145 offset:38912
	ds_read_b128 v[224:227], v145 offset:39936
	global_load_lds_dwordx4 v132, s[22:23]
	s_mov_b32 m0, s34
	s_nop 0
	global_load_lds_dwordx4 v130, s[22:23]
	s_waitcnt lgkmcnt(8)
	s_barrier
	s_waitcnt lgkmcnt(0)
	s_waitcnt lgkmcnt(0)
	v_mfma_f32_16x16x32_bf16 v[124:127], v[138:141], v[172:175], v[124:127]
	v_mfma_f32_16x16x32_bf16 v[120:123], v[164:167], v[172:175], v[120:123]
	v_mfma_f32_16x16x32_bf16 v[116:119], v[138:141], v[204:207], v[116:119]
	v_mfma_f32_16x16x32_bf16 v[108:111], v[164:167], v[204:207], v[108:111]
	v_mfma_f32_16x16x32_bf16 v[100:103], v[138:141], v[212:215], v[100:103]
	v_mfma_f32_16x16x32_bf16 v[92:95], v[164:167], v[212:215], v[92:95]
	v_mfma_f32_16x16x32_bf16 v[84:87], v[138:141], v[220:223], v[84:87]
	v_mfma_f32_16x16x32_bf16 v[76:79], v[164:167], v[220:223], v[76:79]
	v_mfma_f32_16x16x32_bf16 v[124:127], v[160:163], v[200:203], v[124:127]
	v_mfma_f32_16x16x32_bf16 v[120:123], v[168:171], v[200:203], v[120:123]
	v_mfma_f32_16x16x32_bf16 v[116:119], v[160:163], v[208:211], v[116:119]
	v_mfma_f32_16x16x32_bf16 v[108:111], v[168:171], v[208:211], v[108:111]
	v_mfma_f32_16x16x32_bf16 v[100:103], v[160:163], v[216:219], v[100:103]
	v_mfma_f32_16x16x32_bf16 v[92:95], v[168:171], v[216:219], v[92:95]
	v_mfma_f32_16x16x32_bf16 v[84:87], v[160:163], v[224:227], v[84:87]
	v_mfma_f32_16x16x32_bf16 v[76:79], v[168:171], v[224:227], v[76:79]
	s_barrier
	s_add_i32 s22, 0, 0x1c000
	s_add_i32 s23, s45, s29
	v_add_u32_e32 v240, s22, v143
	s_mov_b32 m0, s23
	ds_read_b128 v[228:231], v240
	ds_read_b128 v[232:235], v240 offset:1024
	ds_read_b128 v[236:239], v240 offset:2048
	ds_read_b128 v[240:243], v240 offset:3072
	global_load_lds_dwordx4 v148, s[84:85]
	s_add_i32 m0, s23, 0x2000
	s_nop 0
	global_load_lds_dwordx4 v128, s[84:85]
	s_barrier
	s_waitcnt lgkmcnt(0)
	s_waitcnt lgkmcnt(0)
	v_mfma_f32_16x16x32_bf16 v[112:115], v[228:231], v[172:175], v[112:115]
	v_mfma_f32_16x16x32_bf16 v[104:107], v[236:239], v[172:175], v[104:107]
	v_mfma_f32_16x16x32_bf16 v[96:99], v[228:231], v[204:207], v[96:99]
	v_mfma_f32_16x16x32_bf16 v[88:91], v[236:239], v[204:207], v[88:91]
	v_mfma_f32_16x16x32_bf16 v[80:83], v[228:231], v[212:215], v[80:83]
	v_mfma_f32_16x16x32_bf16 v[72:75], v[236:239], v[212:215], v[72:75]
	v_mfma_f32_16x16x32_bf16 v[68:71], v[228:231], v[220:223], v[68:71]
	v_mfma_f32_16x16x32_bf16 v[64:67], v[236:239], v[220:223], v[64:67]
	v_mfma_f32_16x16x32_bf16 v[112:115], v[232:235], v[200:203], v[112:115]
	v_mfma_f32_16x16x32_bf16 v[104:107], v[240:243], v[200:203], v[104:107]
	v_mfma_f32_16x16x32_bf16 v[96:99], v[232:235], v[208:211], v[96:99]
	v_mfma_f32_16x16x32_bf16 v[88:91], v[240:243], v[208:211], v[88:91]
	v_mfma_f32_16x16x32_bf16 v[80:83], v[232:235], v[216:219], v[80:83]
	v_mfma_f32_16x16x32_bf16 v[72:75], v[240:243], v[216:219], v[72:75]
	v_mfma_f32_16x16x32_bf16 v[68:71], v[232:235], v[224:227], v[68:71]
	v_mfma_f32_16x16x32_bf16 v[64:67], v[240:243], v[224:227], v[64:67]
	s_mov_b32 m0, s35
	s_barrier
	ds_read_b128 v[172:175], v145 offset:49152
	ds_read_b128 v[200:203], v145 offset:50176
	ds_read_b128 v[204:207], v145 offset:51200
	ds_read_b128 v[208:211], v145 offset:52224
	ds_read_b128 v[212:215], v145 offset:53248
	ds_read_b128 v[216:219], v145 offset:54272
	ds_read_b128 v[220:223], v145 offset:55296
	ds_read_b128 v[224:227], v145 offset:56320
	global_load_lds_dwordx4 v132, s[86:87]
	s_mov_b32 m0, s36
	s_nop 0
	global_load_lds_dwordx4 v130, s[86:87]
	s_barrier
; #define PG8_STAGE(bufoff, gbase, voff) do { _Pragma("unroll") for (int _i = 0; _i < 2; ++_i) \
;         __builtin_amdgcn_global_load_lds((const unsigned*)((const char*)(gbase) + (voff)[_i]), (LAS unsigned*)(lds + (bufoff) + ldsw + _i * 8192), 16, 0, 0); } while (0)
; #define PG8_MMA(ai, bj, At, Bt) do { __builtin_amdgcn_s_setprio(1); _Pragma("unroll") for (int m = 0; m < 4; ++m) _Pragma("unroll") for (int n = 0; n < 2; ++n) _Pragma("unroll") for (int k = 0; k < 2; ++k) \
;         acc[ai][bj][m][n] = __builtin_amdgcn_mfma_f32_16x16x32_bf16(Bt[n][k], At[m][k], acc[ai][bj][m][n], 0, 0, 0); __builtin_amdgcn_s_setprio(0); } while (0)
; #define PG8_WAIT_V(n) asm volatile("s_waitcnt vmcnt(" #n ")" ::: "memory")
; #define PG8_WAIT_L(n) asm volatile("s_waitcnt lgkmcnt(" #n ")" ::: "memory")
; #define PG8_BAR __builtin_amdgcn_s_barrier()
; #define PG8_SCHED __builtin_amdgcn_sched_barrier(0)
; template <class Epi, class Sched>
; __device__ __forceinline__ void gemm_phase(LAS unsigned char* lds, const Gemm g, const Sched& S, const Epi& E) {
;     ...
;             PG8_BAR; PG8_WAIT_L(0); PG8_MMA(1, 0, At, B0); PG8_BAR; PG8_SCHED;
;             PG8_STAGE(PG8_SB(1, 1), b3 + hstep, voffB);
;             PG8_WAIT_V(6); PG8_BAR; PG8_MMA(1, 1, At, B1); PG8_BAR;
;         }
	s_waitcnt lgkmcnt(0)
	s_waitcnt lgkmcnt(0)
	v_mfma_f32_16x16x32_bf16 v[60:63], v[138:141], v[172:175], v[60:63]
	v_mfma_f32_16x16x32_bf16 v[56:59], v[164:167], v[172:175], v[56:59]
	v_mfma_f32_16x16x32_bf16 v[52:55], v[138:141], v[204:207], v[52:55]
	v_mfma_f32_16x16x32_bf16 v[44:47], v[164:167], v[204:207], v[44:47]
	v_mfma_f32_16x16x32_bf16 v[36:39], v[138:141], v[212:215], v[36:39]
	v_mfma_f32_16x16x32_bf16 v[28:31], v[164:167], v[212:215], v[28:31]
	v_mfma_f32_16x16x32_bf16 v[20:23], v[138:141], v[220:223], v[20:23]
	v_mfma_f32_16x16x32_bf16 v[12:15], v[164:167], v[220:223], v[12:15]
	v_mfma_f32_16x16x32_bf16 v[60:63], v[160:163], v[200:203], v[60:63]
	v_mfma_f32_16x16x32_bf16 v[56:59], v[168:171], v[200:203], v[56:59]
	v_mfma_f32_16x16x32_bf16 v[52:55], v[160:163], v[208:211], v[52:55]
	v_mfma_f32_16x16x32_bf16 v[44:47], v[168:171], v[208:211], v[44:47]
	v_mfma_f32_16x16x32_bf16 v[36:39], v[160:163], v[216:219], v[36:39]
	v_mfma_f32_16x16x32_bf16 v[28:31], v[168:171], v[216:219], v[28:31]
	v_mfma_f32_16x16x32_bf16 v[20:23], v[160:163], v[224:227], v[20:23]
	v_mfma_f32_16x16x32_bf16 v[12:15], v[168:171], v[224:227], v[12:15]
	s_barrier
	s_add_u32 s20, s20, 0x80080
	s_addc_u32 s21, s21, 0
	s_add_i32 s22, s22, s29
	s_mov_b32 m0, s22
	s_nop 0
	global_load_lds_dwordx4 v148, s[20:21]
	s_add_i32 m0, s22, 0x2000
	s_nop 0
	global_load_lds_dwordx4 v128, s[20:21]
	s_waitcnt vmcnt(6)
	s_barrier
	v_mfma_f32_16x16x32_bf16 v[48:51], v[228:231], v[172:175], v[48:51]
	v_mfma_f32_16x16x32_bf16 v[40:43], v[236:239], v[172:175], v[40:43]
	v_mfma_f32_16x16x32_bf16 v[32:35], v[228:231], v[204:207], v[32:35]
	v_mfma_f32_16x16x32_bf16 v[24:27], v[236:239], v[204:207], v[24:27]
	v_mfma_f32_16x16x32_bf16 v[16:19], v[228:231], v[212:215], v[16:19]
	v_mfma_f32_16x16x32_bf16 v[8:11], v[236:239], v[212:215], v[8:11]
	v_mfma_f32_16x16x32_bf16 v[4:7], v[228:231], v[220:223], v[4:7]
	v_mfma_f32_16x16x32_bf16 v[0:3], v[236:239], v[220:223], v[0:3]
	v_mfma_f32_16x16x32_bf16 v[48:51], v[232:235], v[200:203], v[48:51]
	v_mfma_f32_16x16x32_bf16 v[40:43], v[240:243], v[200:203], v[40:43]
	v_mfma_f32_16x16x32_bf16 v[32:35], v[232:235], v[208:211], v[32:35]
	v_mfma_f32_16x16x32_bf16 v[24:27], v[240:243], v[208:211], v[24:27]
	v_mfma_f32_16x16x32_bf16 v[16:19], v[232:235], v[216:219], v[16:19]
	v_mfma_f32_16x16x32_bf16 v[8:11], v[240:243], v[216:219], v[8:11]
	v_mfma_f32_16x16x32_bf16 v[4:7], v[232:235], v[224:227], v[4:7]
	v_mfma_f32_16x16x32_bf16 v[0:3], v[240:243], v[224:227], v[0:3]
	s_add_i32 s44, s44, 2
	s_add_u32 s16, s16, 0x100
	s_addc_u32 s17, s17, 0
	s_add_u32 s42, s42, 0x100
	s_addc_u32 s43, s43, 0
	s_cmp_gt_u32 s44, 29
	s_barrier
	s_cbranch_scc0 .LBB0_125
; __device__ __forceinline__ unsigned cvt_pk_bf16(float lo, float hi) { unsigned r; asm("v_cvt_pk_bf16_f32 %0, %1, %2" : "=v"(r) : "v"(lo), "v"(hi)); return r; }
; #define PG8_WAIT_V(n) asm volatile("s_waitcnt vmcnt(" #n ")" ::: "memory")
; #define PG8_BAR __builtin_amdgcn_s_barrier()
;     __device__ __forceinline__ void operator()(const f32x4 (&acc)[2][2][4][2], const Unit& u, int wr, int wc, int fr, int fq) const {
;         const int row0 = u.pm * BM + wr * 64 + fr, col0 = u.pn * BM + wc * 32 + 8 * fq;
; #pragma unroll
;         for (int ai = 0; ai < 2; ++ai)
; #pragma unroll
;             for (int m = 0; m < 4; ++m) { bf16_t* rowp = O + (size_t)(row0 + ai * HALF + m * 16) * ldc + col0;
; #pragma unroll
;                 for (int bj = 0; bj < 2; ++bj) { const f32x4 v0 = acc[ai][bj][m][0], v1 = acc[ai][bj][m][1];
;                     u32x4 w; w.x = cvt_pk_bf16(v0[0], v0[1]); w.y = cvt_pk_bf16(v0[2], v0[3]); w.z = cvt_pk_bf16(v1[0], v1[1]); w.w = cvt_pk_bf16(v1[2], v1[3]);
;                     *(u32x4*)(rowp + bj * HALF) = w; } }
;     }
; template <class Epi, class Sched>
; __device__ __forceinline__ void gemm_phase(LAS unsigned char* lds, const Gemm g, const Sched& S, const Epi& E) {
;     ...
;         E(acc, cur, wr, wc, fr, fq);
;         if (!has_next) break;
; #pragma unroll
;         for (int a = 0; a < 2; ++a)
; #pragma unroll
;             for (int b = 0; b < 2; ++b)
; #pragma unroll
;                 for (int m = 0; m < 4; ++m)
; #pragma unroll
;                     for (int n = 0; n < 2; ++n) acc[a][b][m][n] = (f32x4){0.f, 0.f, 0.f, 0.f};
;         cur = nxt; cA = nA; cB = nB; ++ui;
;     }
;     PG8_WAIT_V(0);
;     if (wr == 0) PG8_BAR;
	v_lshl_add_u32 v160, s39, 8, v142
	v_lshl_or_b32 v140, s38, 8, v144
	v_ashrrev_i32_e32 v141, 31, v140
	v_mov_b64_e32 v[138:139], s[2:3]
	v_cvt_pk_bf16_f32 v68, v68, v69
	v_cvt_pk_bf16_f32 v69, v70, v71
	v_cvt_pk_bf16_f32 v70, v64, v65
	v_add_u32_e32 v64, 0x80, v160
	v_mad_i64_i32 v[146:147], s[16:17], v160, s56, v[138:139]
	v_lshlrev_b64 v[140:141], 1, v[140:141]
	v_cvt_pk_bf16_f32 v112, v112, v113
	v_cvt_pk_bf16_f32 v113, v114, v115
	v_cvt_pk_bf16_f32 v114, v104, v105
	v_or_b32_e32 v104, 16, v160
	v_mad_i64_i32 v[64:65], s[16:17], v64, s56, v[138:139]
	v_cvt_pk_bf16_f32 v48, v48, v49
	v_cvt_pk_bf16_f32 v49, v50, v51
	v_cvt_pk_bf16_f32 v50, v40, v41
	v_add_u32_e32 v40, 0x90, v160
	v_lshl_add_u64 v[146:147], v[146:147], 0, v[140:141]
	v_mad_i64_i32 v[104:105], s[16:17], v104, s56, v[138:139]
	v_cvt_pk_bf16_f32 v96, v96, v97
	v_cvt_pk_bf16_f32 v97, v98, v99
	v_cvt_pk_bf16_f32 v98, v88, v89
	v_or_b32_e32 v88, 32, v160
	v_lshl_add_u64 v[64:65], v[64:65], 0, v[140:141]
	v_mad_i64_i32 v[40:41], s[16:17], v40, s56, v[138:139]
	v_cvt_pk_bf16_f32 v32, v32, v33
	v_cvt_pk_bf16_f32 v33, v34, v35
	v_cvt_pk_bf16_f32 v34, v24, v25
	v_add_u32_e32 v24, 0xa0, v160
	v_cvt_pk_bf16_f32 v115, v106, v107
	global_store_dwordx4 v[146:147], v[112:115], off offset:256
	v_mad_i64_i32 v[88:89], s[16:17], v88, s56, v[138:139]
	s_nop 0
	v_lshl_add_u64 v[112:113], v[104:105], 0, v[140:141]
	v_cvt_pk_bf16_f32 v80, v80, v81
	v_cvt_pk_bf16_f32 v81, v82, v83
	v_cvt_pk_bf16_f32 v82, v72, v73
	v_or_b32_e32 v72, 48, v160
	v_cvt_pk_bf16_f32 v51, v42, v43
	global_store_dwordx4 v[64:65], v[48:51], off offset:256
	v_mad_i64_i32 v[24:25], s[16:17], v24, s56, v[138:139]
	s_nop 0
	v_lshl_add_u64 v[48:49], v[40:41], 0, v[140:141]
	v_cvt_pk_bf16_f32 v16, v16, v17
	v_cvt_pk_bf16_f32 v17, v18, v19
	v_cvt_pk_bf16_f32 v18, v8, v9
	v_add_u32_e32 v8, 0xb0, v160
	v_cvt_pk_bf16_f32 v99, v90, v91
	global_store_dwordx4 v[112:113], v[96:99], off offset:256
	v_mad_i64_i32 v[72:73], s[16:17], v72, s56, v[138:139]
	s_nop 0
	v_lshl_add_u64 v[96:97], v[88:89], 0, v[140:141]
	v_cvt_pk_bf16_f32 v35, v26, v27
	global_store_dwordx4 v[48:49], v[32:35], off offset:256
	v_mad_i64_i32 v[8:9], s[16:17], v8, s56, v[138:139]
	s_nop 0
	v_lshl_add_u64 v[32:33], v[24:25], 0, v[140:141]
	v_cvt_pk_bf16_f32 v83, v74, v75
	global_store_dwordx4 v[96:97], v[80:83], off offset:256
	v_cvt_pk_bf16_f32 v19, v10, v11
	global_store_dwordx4 v[32:33], v[16:19], off offset:256
	s_and_b64 vcc, exec, s[0:1]
	v_lshl_add_u64 v[80:81], v[72:73], 0, v[140:141]
	v_lshl_add_u64 v[16:17], v[8:9], 0, v[140:141]
	s_mov_b32 s38, s4
	s_mov_b32 s39, s6
	s_mov_b64 s[20:21], s[14:15]
	s_mov_b64 s[16:17], s[12:13]
	v_cvt_pk_bf16_f32 v124, v124, v125
	v_cvt_pk_bf16_f32 v125, v126, v127
	v_cvt_pk_bf16_f32 v126, v120, v121
	v_cvt_pk_bf16_f32 v127, v122, v123
	global_store_dwordx4 v[146:147], v[124:127], off
	v_cvt_pk_bf16_f32 v104, v116, v117
	v_cvt_pk_bf16_f32 v105, v118, v119
	v_cvt_pk_bf16_f32 v106, v108, v109
	v_cvt_pk_bf16_f32 v107, v110, v111
	global_store_dwordx4 v[112:113], v[104:107], off
	v_cvt_pk_bf16_f32 v88, v100, v101
	v_cvt_pk_bf16_f32 v89, v102, v103
	v_cvt_pk_bf16_f32 v90, v92, v93
	v_cvt_pk_bf16_f32 v91, v94, v95
	global_store_dwordx4 v[96:97], v[88:91], off
	v_cvt_pk_bf16_f32 v72, v84, v85
	v_cvt_pk_bf16_f32 v73, v86, v87
	v_cvt_pk_bf16_f32 v74, v76, v77
	v_cvt_pk_bf16_f32 v75, v78, v79
	global_store_dwordx4 v[80:81], v[72:75], off
	v_cvt_pk_bf16_f32 v71, v66, v67
	global_store_dwordx4 v[80:81], v[68:71], off offset:256
	v_cvt_pk_bf16_f32 v60, v60, v61
	v_cvt_pk_bf16_f32 v61, v62, v63
	v_cvt_pk_bf16_f32 v62, v56, v57
	v_cvt_pk_bf16_f32 v63, v58, v59
	global_store_dwordx4 v[64:65], v[60:63], off
	v_cvt_pk_bf16_f32 v40, v52, v53
	v_cvt_pk_bf16_f32 v41, v54, v55
	v_cvt_pk_bf16_f32 v42, v44, v45
	v_cvt_pk_bf16_f32 v43, v46, v47
	global_store_dwordx4 v[48:49], v[40:43], off
	v_cvt_pk_bf16_f32 v24, v36, v37
	v_cvt_pk_bf16_f32 v25, v38, v39
	v_cvt_pk_bf16_f32 v26, v28, v29
	v_cvt_pk_bf16_f32 v27, v30, v31
	global_store_dwordx4 v[32:33], v[24:27], off
	v_cvt_pk_bf16_f32 v8, v20, v21
	v_cvt_pk_bf16_f32 v9, v22, v23
	v_cvt_pk_bf16_f32 v10, v12, v13
	v_cvt_pk_bf16_f32 v11, v14, v15
	global_store_dwordx4 v[16:17], v[8:11], off
	v_cvt_pk_bf16_f32 v4, v4, v5
	v_cvt_pk_bf16_f32 v5, v6, v7
	v_cvt_pk_bf16_f32 v6, v0, v1
	v_cvt_pk_bf16_f32 v7, v2, v3
	global_store_dwordx4 v[16:17], v[4:7], off offset:256
	s_cbranch_vccz .LBB0_118
	s_waitcnt vmcnt(0)
	s_cmpk_gt_u32 s24, 0xff
	s_cbranch_scc1 .LBB0_129
	s_barrier

; #define PG8_STAGE(bufoff, gbase, voff) do { _Pragma("unroll") for (int _i = 0; _i < 2; ++_i) \
;         __builtin_amdgcn_global_load_lds((const unsigned*)((const char*)(gbase) + (voff)[_i]), (LAS unsigned*)(lds + (bufoff) + ldsw + _i * 8192), 16, 0, 0); } while (0)
; #define PG8_LDA(dst, b, h) do { _Pragma("unroll") for (int m = 0; m < 4; ++m) _Pragma("unroll") for (int k = 0; k < 2; ++k) dst[m][k] = *(const LAS bf16x8*)(lds + PG8_SA(b, h) + aoff + m * 2048 + k * 1024); } while (0)
; #define PG8_LDB(dst, b, h) do { _Pragma("unroll") for (int n = 0; n < 2; ++n) _Pragma("unroll") for (int k = 0; k < 2; ++k) dst[n][k] = *(const LAS bf16x8*)(lds + PG8_SB(b, h) + boff + n * 2048 + k * 1024); } while (0)
; #define PG8_MMA(ai, bj, At, Bt) do { __builtin_amdgcn_s_setprio(1); _Pragma("unroll") for (int m = 0; m < 4; ++m) _Pragma("unroll") for (int n = 0; n < 2; ++n) _Pragma("unroll") for (int k = 0; k < 2; ++k) \
;         acc[ai][bj][m][n] = __builtin_amdgcn_mfma_f32_16x16x32_bf16(Bt[n][k], At[m][k], acc[ai][bj][m][n], 0, 0, 0); __builtin_amdgcn_s_setprio(0); } while (0)
; #define PG8_WAIT_V(n) asm volatile("s_waitcnt vmcnt(" #n ")" ::: "memory")
; #define PG8_WAIT_L(n) asm volatile("s_waitcnt lgkmcnt(" #n ")" ::: "memory")
; template <class Epi, class Sched>
; __device__ __forceinline__ void gemm_phase(LAS unsigned char* lds, const Gemm g, const Sched& S, const Epi& E) {
;     ...
;         for (int t = 0; t < nt; t += 2) {
;             const bool last = (t == nt - 2);
;             const char* a1 = cA + (size_t)(t + 1) * kstep;
;             const char* a2 = last ? nA : cA + (size_t)(t + 2) * kstep; const char* b2 = last ? nB : cB + (size_t)(t + 2) * kstep;
;             const char* a3 = a2 + kstep; const char* b3 = b2 + kstep;
;             PG8_LDB(B0, 0, 0); PG8_SCHED; PG8_LDA(At, 0, 0); PG8_STAGE(PG8_SA(1, 1), a1 + hstep, voffA);
;             PG8_WAIT_L(8); PG8_BAR; PG8_WAIT_L(0); PG8_MMA(0, 0, At, B0); PG8_BAR; PG8_SCHED;
;             PG8_LDB(B1, 0, 1); PG8_STAGE(PG8_SB(0, 0), b2, voffB);
;             PG8_BAR; PG8_WAIT_L(0); PG8_MMA(0, 1, At, B1); PG8_BAR;
;             PG8_LDA(At, 0, 1); PG8_STAGE(PG8_SA(0, 0), a2, voffA);
;             PG8_BAR; PG8_WAIT_L(0); PG8_MMA(1, 0, At, B0); PG8_BAR; PG8_SCHED;
;             PG8_STAGE(PG8_SB(0, 1), b2 + hstep, voffB);
;             PG8_WAIT_V(6); PG8_BAR; PG8_MMA(1, 1, At, B1); PG8_BAR;
.LBB0_170:
	s_add_i32 s53, s22, 2
	s_add_u32 s20, s16, 0x100
	s_addc_u32 s21, s17, 0
	s_add_i32 s54, 0, 0x10000
	v_add_u32_e32 v146, s54, v171
	ds_read_b128 v[128:131], v146
	ds_read_b128 v[132:135], v146 offset:1024
	ds_read_b128 v[136:139], v146 offset:2048
	ds_read_b128 v[160:163], v146 offset:3072
	s_cmp_eq_u32 s15, s22
	s_cselect_b32 s22, s4, s51
	s_cselect_b32 s25, s7, s21
	s_cselect_b32 s24, s6, s20
	s_cselect_b32 s23, s5, s52
	s_add_i32 m0, s35, 0xc000
	ds_read_b128 v[164:167], v173
	ds_read_b128 v[174:177], v173 offset:1024
	ds_read_b128 v[200:203], v173 offset:2048
	ds_read_b128 v[204:207], v173 offset:3072
	ds_read_b128 v[208:211], v173 offset:4096
	ds_read_b128 v[212:215], v173 offset:5120
	ds_read_b128 v[216:219], v173 offset:6144
	ds_read_b128 v[220:223], v173 offset:7168
	global_load_lds_dwordx4 v142, s[16:17]
	s_add_i32 m0, s35, 0xe000
	s_nop 0
	global_load_lds_dwordx4 v144, s[16:17]
	s_waitcnt lgkmcnt(8)
	s_barrier
	s_waitcnt lgkmcnt(0)
	s_waitcnt lgkmcnt(0)
	v_mfma_f32_16x16x32_bf16 v[124:127], v[128:131], v[164:167], v[124:127]
	v_mfma_f32_16x16x32_bf16 v[120:123], v[136:139], v[164:167], v[120:123]
	v_mfma_f32_16x16x32_bf16 v[116:119], v[128:131], v[200:203], v[116:119]
	v_mfma_f32_16x16x32_bf16 v[112:115], v[136:139], v[200:203], v[112:115]
	v_mfma_f32_16x16x32_bf16 v[100:103], v[128:131], v[208:211], v[100:103]
	v_mfma_f32_16x16x32_bf16 v[96:99], v[136:139], v[208:211], v[96:99]
	v_mfma_f32_16x16x32_bf16 v[84:87], v[128:131], v[216:219], v[84:87]
	v_mfma_f32_16x16x32_bf16 v[80:83], v[136:139], v[216:219], v[80:83]
	v_mfma_f32_16x16x32_bf16 v[124:127], v[132:135], v[174:177], v[124:127]
	v_mfma_f32_16x16x32_bf16 v[120:123], v[160:163], v[174:177], v[120:123]
	v_mfma_f32_16x16x32_bf16 v[116:119], v[132:135], v[204:207], v[116:119]
	v_mfma_f32_16x16x32_bf16 v[112:115], v[160:163], v[204:207], v[112:115]
	v_mfma_f32_16x16x32_bf16 v[100:103], v[132:135], v[212:215], v[100:103]
	v_mfma_f32_16x16x32_bf16 v[96:99], v[160:163], v[212:215], v[96:99]
	v_mfma_f32_16x16x32_bf16 v[84:87], v[132:135], v[220:223], v[84:87]
	v_mfma_f32_16x16x32_bf16 v[80:83], v[160:163], v[220:223], v[80:83]
	s_barrier
	s_add_i32 s55, 0, 0x14000
	v_add_u32_e32 v146, s55, v171
	s_add_i32 s16, s54, s29
	ds_read_b128 v[224:227], v146
	ds_read_b128 v[228:231], v146 offset:1024
	ds_read_b128 v[232:235], v146 offset:2048
	ds_read_b128 v[236:239], v146 offset:3072
	s_add_u32 s84, s22, 0x80
	s_addc_u32 s85, s23, 0
	s_mov_b32 m0, s16
	s_nop 0
	global_load_lds_dwordx4 v148, s[22:23]
	s_add_i32 m0, s16, 0x2000
	s_nop 0
	global_load_lds_dwordx4 v140, s[22:23]
	s_barrier
	s_waitcnt lgkmcnt(0)
	s_waitcnt lgkmcnt(0)
	v_mfma_f32_16x16x32_bf16 v[108:111], v[224:227], v[164:167], v[108:111]
	v_mfma_f32_16x16x32_bf16 v[104:107], v[232:235], v[164:167], v[104:107]
	v_mfma_f32_16x16x32_bf16 v[92:95], v[224:227], v[200:203], v[92:95]
	v_mfma_f32_16x16x32_bf16 v[88:91], v[232:235], v[200:203], v[88:91]
	v_mfma_f32_16x16x32_bf16 v[76:79], v[224:227], v[208:211], v[76:79]
	v_mfma_f32_16x16x32_bf16 v[72:75], v[232:235], v[208:211], v[72:75]
	v_mfma_f32_16x16x32_bf16 v[68:71], v[224:227], v[216:219], v[68:71]
	v_mfma_f32_16x16x32_bf16 v[64:67], v[232:235], v[216:219], v[64:67]
	v_mfma_f32_16x16x32_bf16 v[108:111], v[228:231], v[174:177], v[108:111]
	v_mfma_f32_16x16x32_bf16 v[104:107], v[236:239], v[174:177], v[104:107]
	v_mfma_f32_16x16x32_bf16 v[92:95], v[228:231], v[204:207], v[92:95]
	v_mfma_f32_16x16x32_bf16 v[88:91], v[236:239], v[204:207], v[88:91]
	v_mfma_f32_16x16x32_bf16 v[76:79], v[228:231], v[212:215], v[76:79]
	v_mfma_f32_16x16x32_bf16 v[72:75], v[236:239], v[212:215], v[72:75]
	v_mfma_f32_16x16x32_bf16 v[68:71], v[228:231], v[220:223], v[68:71]
	v_mfma_f32_16x16x32_bf16 v[64:67], v[236:239], v[220:223], v[64:67]
	s_mov_b32 m0, s35
	s_add_u32 s86, s24, 0x80
	s_addc_u32 s87, s25, 0
	s_barrier
	ds_read_b128 v[164:167], v173 offset:16384
	ds_read_b128 v[174:177], v173 offset:17408
	ds_read_b128 v[200:203], v173 offset:18432
	ds_read_b128 v[204:207], v173 offset:19456
	ds_read_b128 v[208:211], v173 offset:20480
	ds_read_b128 v[212:215], v173 offset:21504
	ds_read_b128 v[216:219], v173 offset:22528
	ds_read_b128 v[220:223], v173 offset:23552
	global_load_lds_dwordx4 v148, s[24:25]
	s_mov_b32 m0, s36
	s_nop 0
	global_load_lds_dwordx4 v140, s[24:25]
	s_barrier
	s_waitcnt lgkmcnt(0)
	s_waitcnt lgkmcnt(0)
	v_mfma_f32_16x16x32_bf16 v[60:63], v[128:131], v[164:167], v[60:63]
	v_mfma_f32_16x16x32_bf16 v[56:59], v[136:139], v[164:167], v[56:59]
	v_mfma_f32_16x16x32_bf16 v[52:55], v[128:131], v[200:203], v[52:55]
	v_mfma_f32_16x16x32_bf16 v[48:51], v[136:139], v[200:203], v[48:51]
	v_mfma_f32_16x16x32_bf16 v[36:39], v[128:131], v[208:211], v[36:39]
	v_mfma_f32_16x16x32_bf16 v[32:35], v[136:139], v[208:211], v[32:35]
	v_mfma_f32_16x16x32_bf16 v[20:23], v[128:131], v[216:219], v[20:23]
	v_mfma_f32_16x16x32_bf16 v[16:19], v[136:139], v[216:219], v[16:19]
	v_mfma_f32_16x16x32_bf16 v[60:63], v[132:135], v[174:177], v[60:63]
	v_mfma_f32_16x16x32_bf16 v[56:59], v[160:163], v[174:177], v[56:59]
	v_mfma_f32_16x16x32_bf16 v[52:55], v[132:135], v[204:207], v[52:55]
	v_mfma_f32_16x16x32_bf16 v[48:51], v[160:163], v[204:207], v[48:51]
	v_mfma_f32_16x16x32_bf16 v[36:39], v[132:135], v[212:215], v[36:39]
	v_mfma_f32_16x16x32_bf16 v[32:35], v[160:163], v[212:215], v[32:35]
	v_mfma_f32_16x16x32_bf16 v[20:23], v[132:135], v[220:223], v[20:23]
	v_mfma_f32_16x16x32_bf16 v[16:19], v[160:163], v[220:223], v[16:19]
	s_barrier
	s_add_u32 s16, s22, 0x160000
	s_addc_u32 s17, s23, 0
	s_add_i32 s54, s55, s29
	s_mov_b32 m0, s54
	s_nop 0
	global_load_lds_dwordx4 v148, s[16:17]
	s_add_i32 m0, s54, 0x2000
	s_nop 0
	global_load_lds_dwordx4 v140, s[16:17]
	s_waitcnt vmcnt(6)
	s_barrier
; #define PG8_STAGE(bufoff, gbase, voff) do { _Pragma("unroll") for (int _i = 0; _i < 2; ++_i) \
;         __builtin_amdgcn_global_load_lds((const unsigned*)((const char*)(gbase) + (voff)[_i]), (LAS unsigned*)(lds + (bufoff) + ldsw + _i * 8192), 16, 0, 0); } while (0)
; #define PG8_LDA(dst, b, h) do { _Pragma("unroll") for (int m = 0; m < 4; ++m) _Pragma("unroll") for (int k = 0; k < 2; ++k) dst[m][k] = *(const LAS bf16x8*)(lds + PG8_SA(b, h) + aoff + m * 2048 + k * 1024); } while (0)
; #define PG8_LDB(dst, b, h) do { _Pragma("unroll") for (int n = 0; n < 2; ++n) _Pragma("unroll") for (int k = 0; k < 2; ++k) dst[n][k] = *(const LAS bf16x8*)(lds + PG8_SB(b, h) + boff + n * 2048 + k * 1024); } while (0)
; #define PG8_MMA(ai, bj, At, Bt) do { __builtin_amdgcn_s_setprio(1); _Pragma("unroll") for (int m = 0; m < 4; ++m) _Pragma("unroll") for (int n = 0; n < 2; ++n) _Pragma("unroll") for (int k = 0; k < 2; ++k) \
;         acc[ai][bj][m][n] = __builtin_amdgcn_mfma_f32_16x16x32_bf16(Bt[n][k], At[m][k], acc[ai][bj][m][n], 0, 0, 0); __builtin_amdgcn_s_setprio(0); } while (0)
; #define PG8_WAIT_L(n) asm volatile("s_waitcnt lgkmcnt(" #n ")" ::: "memory")
; #define PG8_BAR __builtin_amdgcn_s_barrier()
; #define PG8_SCHED __builtin_amdgcn_sched_barrier(0)
; template <class Epi, class Sched>
; __device__ __forceinline__ void gemm_phase(LAS unsigned char* lds, const Gemm g, const Sched& S, const Epi& E) {
;     ...
;             PG8_LDB(B0, 1, 0); PG8_SCHED; PG8_LDA(At, 1, 0); PG8_STAGE(PG8_SA(0, 1), a2 + hstep, voffA);
;             PG8_WAIT_L(8); PG8_BAR; PG8_WAIT_L(0); PG8_MMA(0, 0, At, B0); PG8_BAR; PG8_SCHED;
;             PG8_LDB(B1, 1, 1); PG8_STAGE(PG8_SB(1, 0), b3, voffB);
;             PG8_BAR; PG8_WAIT_L(0); PG8_MMA(0, 1, At, B1); PG8_BAR;
;             PG8_LDA(At, 1, 1); PG8_STAGE(PG8_SA(1, 0), a3, voffA);
;             PG8_BAR; PG8_WAIT_L(0); PG8_MMA(1, 0, At, B0); PG8_BAR; PG8_SCHED;
	v_mfma_f32_16x16x32_bf16 v[44:47], v[224:227], v[164:167], v[44:47]
	v_mfma_f32_16x16x32_bf16 v[40:43], v[232:235], v[164:167], v[40:43]
	v_mfma_f32_16x16x32_bf16 v[28:31], v[224:227], v[200:203], v[28:31]
	v_mfma_f32_16x16x32_bf16 v[24:27], v[232:235], v[200:203], v[24:27]
	v_mfma_f32_16x16x32_bf16 v[12:15], v[224:227], v[208:211], v[12:15]
	v_mfma_f32_16x16x32_bf16 v[8:11], v[232:235], v[208:211], v[8:11]
	v_mfma_f32_16x16x32_bf16 v[4:7], v[224:227], v[216:219], v[4:7]
	v_mfma_f32_16x16x32_bf16 v[0:3], v[232:235], v[216:219], v[0:3]
	v_mfma_f32_16x16x32_bf16 v[44:47], v[228:231], v[174:177], v[44:47]
	v_mfma_f32_16x16x32_bf16 v[40:43], v[236:239], v[174:177], v[40:43]
	v_mfma_f32_16x16x32_bf16 v[28:31], v[228:231], v[204:207], v[28:31]
	v_mfma_f32_16x16x32_bf16 v[24:27], v[236:239], v[204:207], v[24:27]
	v_mfma_f32_16x16x32_bf16 v[12:15], v[228:231], v[212:215], v[12:15]
	v_mfma_f32_16x16x32_bf16 v[8:11], v[236:239], v[212:215], v[8:11]
	v_mfma_f32_16x16x32_bf16 v[4:7], v[228:231], v[220:223], v[4:7]
	v_mfma_f32_16x16x32_bf16 v[0:3], v[236:239], v[220:223], v[0:3]
	s_add_i32 s54, 0, 0x18000
	v_add_u32_e32 v160, s54, v171
	s_barrier
	ds_read_b128 v[128:131], v160
	ds_read_b128 v[132:135], v160 offset:1024
	ds_read_b128 v[136:139], v160 offset:2048
	ds_read_b128 v[160:163], v160 offset:3072
	s_add_u32 s16, s24, 0x160000
	s_addc_u32 s17, s25, 0
	s_mov_b32 m0, s37
	ds_read_b128 v[164:167], v173 offset:32768
	ds_read_b128 v[174:177], v173 offset:33792
	ds_read_b128 v[200:203], v173 offset:34816
	ds_read_b128 v[204:207], v173 offset:35840
	ds_read_b128 v[208:211], v173 offset:36864
	ds_read_b128 v[212:215], v173 offset:37888
	ds_read_b128 v[216:219], v173 offset:38912
	ds_read_b128 v[220:223], v173 offset:39936
	global_load_lds_dwordx4 v148, s[16:17]
	s_mov_b32 m0, s38
	s_nop 0
	global_load_lds_dwordx4 v140, s[16:17]
	s_waitcnt lgkmcnt(8)
	s_barrier
	s_waitcnt lgkmcnt(0)
	s_waitcnt lgkmcnt(0)
	v_mfma_f32_16x16x32_bf16 v[124:127], v[128:131], v[164:167], v[124:127]
	v_mfma_f32_16x16x32_bf16 v[120:123], v[136:139], v[164:167], v[120:123]
	v_mfma_f32_16x16x32_bf16 v[116:119], v[128:131], v[200:203], v[116:119]
	v_mfma_f32_16x16x32_bf16 v[112:115], v[136:139], v[200:203], v[112:115]
	v_mfma_f32_16x16x32_bf16 v[100:103], v[128:131], v[208:211], v[100:103]
	v_mfma_f32_16x16x32_bf16 v[96:99], v[136:139], v[208:211], v[96:99]
	v_mfma_f32_16x16x32_bf16 v[84:87], v[128:131], v[216:219], v[84:87]
	v_mfma_f32_16x16x32_bf16 v[80:83], v[136:139], v[216:219], v[80:83]
	v_mfma_f32_16x16x32_bf16 v[124:127], v[132:135], v[174:177], v[124:127]
	v_mfma_f32_16x16x32_bf16 v[120:123], v[160:163], v[174:177], v[120:123]
	v_mfma_f32_16x16x32_bf16 v[116:119], v[132:135], v[204:207], v[116:119]
	v_mfma_f32_16x16x32_bf16 v[112:115], v[160:163], v[204:207], v[112:115]
	v_mfma_f32_16x16x32_bf16 v[100:103], v[132:135], v[212:215], v[100:103]
	v_mfma_f32_16x16x32_bf16 v[96:99], v[160:163], v[212:215], v[96:99]
	v_mfma_f32_16x16x32_bf16 v[84:87], v[132:135], v[220:223], v[84:87]
	v_mfma_f32_16x16x32_bf16 v[80:83], v[160:163], v[220:223], v[80:83]
	s_barrier
	s_add_i32 s24, 0, 0x1c000
	s_add_i32 s16, s54, s29
	v_add_u32_e32 v236, s24, v171
	s_mov_b32 m0, s16
	ds_read_b128 v[224:227], v236
	ds_read_b128 v[228:231], v236 offset:1024
	ds_read_b128 v[232:235], v236 offset:2048
	ds_read_b128 v[236:239], v236 offset:3072
	global_load_lds_dwordx4 v148, s[84:85]
	s_add_i32 m0, s16, 0x2000
	s_nop 0
	global_load_lds_dwordx4 v140, s[84:85]
	s_barrier
	s_waitcnt lgkmcnt(0)
	s_waitcnt lgkmcnt(0)
	v_mfma_f32_16x16x32_bf16 v[108:111], v[224:227], v[164:167], v[108:111]
	v_mfma_f32_16x16x32_bf16 v[104:107], v[232:235], v[164:167], v[104:107]
	v_mfma_f32_16x16x32_bf16 v[92:95], v[224:227], v[200:203], v[92:95]
	v_mfma_f32_16x16x32_bf16 v[88:91], v[232:235], v[200:203], v[88:91]
	v_mfma_f32_16x16x32_bf16 v[76:79], v[224:227], v[208:211], v[76:79]
	v_mfma_f32_16x16x32_bf16 v[72:75], v[232:235], v[208:211], v[72:75]
	v_mfma_f32_16x16x32_bf16 v[68:71], v[224:227], v[216:219], v[68:71]
	v_mfma_f32_16x16x32_bf16 v[64:67], v[232:235], v[216:219], v[64:67]
	v_mfma_f32_16x16x32_bf16 v[108:111], v[228:231], v[174:177], v[108:111]
	v_mfma_f32_16x16x32_bf16 v[104:107], v[236:239], v[174:177], v[104:107]
	v_mfma_f32_16x16x32_bf16 v[92:95], v[228:231], v[204:207], v[92:95]
	v_mfma_f32_16x16x32_bf16 v[88:91], v[236:239], v[204:207], v[88:91]
	v_mfma_f32_16x16x32_bf16 v[76:79], v[228:231], v[212:215], v[76:79]
	v_mfma_f32_16x16x32_bf16 v[72:75], v[236:239], v[212:215], v[72:75]
	v_mfma_f32_16x16x32_bf16 v[68:71], v[228:231], v[220:223], v[68:71]
	v_mfma_f32_16x16x32_bf16 v[64:67], v[236:239], v[220:223], v[64:67]
	s_mov_b32 m0, s41
	s_barrier
	ds_read_b128 v[164:167], v173 offset:49152
	ds_read_b128 v[174:177], v173 offset:50176
	ds_read_b128 v[200:203], v173 offset:51200
	ds_read_b128 v[204:207], v173 offset:52224
	ds_read_b128 v[208:211], v173 offset:53248
	ds_read_b128 v[212:215], v173 offset:54272
	ds_read_b128 v[216:219], v173 offset:55296
	ds_read_b128 v[220:223], v173 offset:56320
	global_load_lds_dwordx4 v148, s[86:87]
	s_mov_b32 m0, s42
	s_nop 0
	global_load_lds_dwordx4 v140, s[86:87]
	s_barrier
; #define PG8_STAGE(bufoff, gbase, voff) do { _Pragma("unroll") for (int _i = 0; _i < 2; ++_i) \
;         __builtin_amdgcn_global_load_lds((const unsigned*)((const char*)(gbase) + (voff)[_i]), (LAS unsigned*)(lds + (bufoff) + ldsw + _i * 8192), 16, 0, 0); } while (0)
; #define PG8_MMA(ai, bj, At, Bt) do { __builtin_amdgcn_s_setprio(1); _Pragma("unroll") for (int m = 0; m < 4; ++m) _Pragma("unroll") for (int n = 0; n < 2; ++n) _Pragma("unroll") for (int k = 0; k < 2; ++k) \
;         acc[ai][bj][m][n] = __builtin_amdgcn_mfma_f32_16x16x32_bf16(Bt[n][k], At[m][k], acc[ai][bj][m][n], 0, 0, 0); __builtin_amdgcn_s_setprio(0); } while (0)
; #define PG8_WAIT_V(n) asm volatile("s_waitcnt vmcnt(" #n ")" ::: "memory")
; #define PG8_WAIT_L(n) asm volatile("s_waitcnt lgkmcnt(" #n ")" ::: "memory")
; #define PG8_BAR __builtin_amdgcn_s_barrier()
; #define PG8_SCHED __builtin_amdgcn_sched_barrier(0)
;     __device__ __forceinline__ void operator()(const f32x4 (&acc)[2][2][4][2], const Unit& u, int wr, int wc, int fr, int fq) const {
;     ...
;         const float* base = (u.pm < 32) ? base_lo : base_hi;
; #pragma unroll
;         for (int ai = 0; ai < 2; ++ai) {
;             f32x4 bs[4][2][2];
; #pragma unroll
;             for (int m = 0; m < 4; ++m) { const size_t off = (size_t)(row0 + ai * HALF + m * 16) * DM + col0;
; #pragma unroll
;                 for (int bj = 0; bj < 2; ++bj)
; #pragma unroll
;                     for (int n = 0; n < 2; ++n) bs[m][bj][n] = *(const f32x4*)(base + off + bj * HALF + n * 16); }
; template <class Epi, class Sched>
; __device__ __forceinline__ void gemm_phase(LAS unsigned char* lds, const Gemm g, const Sched& S, const Epi& E) {
;     ...
;             PG8_BAR; PG8_WAIT_L(0); PG8_MMA(1, 0, At, B0); PG8_BAR; PG8_SCHED;
;             PG8_STAGE(PG8_SB(1, 1), b3 + hstep, voffB);
;             PG8_WAIT_V(6); PG8_BAR; PG8_MMA(1, 1, At, B1); PG8_BAR;
;         }
;         E(acc, cur, wr, wc, fr, fq);
;         if (!has_next) break;
	s_waitcnt lgkmcnt(0)
	s_waitcnt lgkmcnt(0)
	v_mfma_f32_16x16x32_bf16 v[60:63], v[128:131], v[164:167], v[60:63]
	v_mfma_f32_16x16x32_bf16 v[56:59], v[136:139], v[164:167], v[56:59]
	v_mfma_f32_16x16x32_bf16 v[52:55], v[128:131], v[200:203], v[52:55]
	v_mfma_f32_16x16x32_bf16 v[48:51], v[136:139], v[200:203], v[48:51]
	v_mfma_f32_16x16x32_bf16 v[36:39], v[128:131], v[208:211], v[36:39]
	v_mfma_f32_16x16x32_bf16 v[32:35], v[136:139], v[208:211], v[32:35]
	v_mfma_f32_16x16x32_bf16 v[20:23], v[128:131], v[216:219], v[20:23]
	v_mfma_f32_16x16x32_bf16 v[16:19], v[136:139], v[216:219], v[16:19]
	v_mfma_f32_16x16x32_bf16 v[60:63], v[132:135], v[174:177], v[60:63]
	v_mfma_f32_16x16x32_bf16 v[56:59], v[160:163], v[174:177], v[56:59]
	v_mfma_f32_16x16x32_bf16 v[52:55], v[132:135], v[204:207], v[52:55]
	v_mfma_f32_16x16x32_bf16 v[48:51], v[160:163], v[204:207], v[48:51]
	v_mfma_f32_16x16x32_bf16 v[36:39], v[132:135], v[212:215], v[36:39]
	v_mfma_f32_16x16x32_bf16 v[32:35], v[160:163], v[212:215], v[32:35]
	v_mfma_f32_16x16x32_bf16 v[20:23], v[132:135], v[220:223], v[20:23]
	v_mfma_f32_16x16x32_bf16 v[16:19], v[160:163], v[220:223], v[16:19]
	s_barrier
	s_add_u32 s16, s22, 0x160080
	s_addc_u32 s17, s23, 0
	s_add_i32 s22, s24, s29
	s_mov_b32 m0, s22
	s_nop 0
	global_load_lds_dwordx4 v148, s[16:17]
	s_add_i32 m0, s22, 0x2000
	s_nop 0
	global_load_lds_dwordx4 v140, s[16:17]
	s_waitcnt vmcnt(6)
	s_barrier
	v_mfma_f32_16x16x32_bf16 v[44:47], v[224:227], v[164:167], v[44:47]
	v_mfma_f32_16x16x32_bf16 v[40:43], v[232:235], v[164:167], v[40:43]
	v_mfma_f32_16x16x32_bf16 v[28:31], v[224:227], v[200:203], v[28:31]
	v_mfma_f32_16x16x32_bf16 v[24:27], v[232:235], v[200:203], v[24:27]
	v_mfma_f32_16x16x32_bf16 v[12:15], v[224:227], v[208:211], v[12:15]
	v_mfma_f32_16x16x32_bf16 v[8:11], v[232:235], v[208:211], v[8:11]
	v_mfma_f32_16x16x32_bf16 v[4:7], v[224:227], v[216:219], v[4:7]
	v_mfma_f32_16x16x32_bf16 v[0:3], v[232:235], v[216:219], v[0:3]
	v_mfma_f32_16x16x32_bf16 v[44:47], v[228:231], v[174:177], v[44:47]
	v_mfma_f32_16x16x32_bf16 v[40:43], v[236:239], v[174:177], v[40:43]
	v_mfma_f32_16x16x32_bf16 v[28:31], v[228:231], v[204:207], v[28:31]
	v_mfma_f32_16x16x32_bf16 v[24:27], v[236:239], v[204:207], v[24:27]
	v_mfma_f32_16x16x32_bf16 v[12:15], v[228:231], v[212:215], v[12:15]
	v_mfma_f32_16x16x32_bf16 v[8:11], v[236:239], v[212:215], v[8:11]
	v_mfma_f32_16x16x32_bf16 v[4:7], v[228:231], v[220:223], v[4:7]
	v_mfma_f32_16x16x32_bf16 v[0:3], v[236:239], v[220:223], v[0:3]
	s_add_u32 s51, s51, 0x100
	s_addc_u32 s52, s52, 0
	s_cmp_ge_i32 s53, s50
	s_mov_b64 s[16:17], s[20:21]
	s_mov_b32 s22, s53
	s_barrier
	s_cbranch_scc0 .LBB0_170
	v_lshl_add_u32 v146, s48, 8, v170
	v_lshl_or_b32 v160, s49, 8, v172
	s_mov_b64 s[16:17], -1
	s_cmp_lt_i32 s82, 0
	v_ashrrev_i32_e32 v161, 31, v160
	v_ashrrev_i32_e32 v147, 31, v146
	s_cbranch_scc0 .LBB0_173
	s_cmp_lt_i32 s48, 32
	s_cselect_b32 s17, s13, s61
	s_cselect_b32 s16, s12, s60
	v_lshlrev_b64 v[162:163], 2, v[160:161]
	v_lshl_add_u64 v[164:165], s[16:17], 0, v[162:163]
	v_lshlrev_b64 v[166:167], 13, v[146:147]
	v_lshl_add_u64 v[128:129], v[164:165], 0, v[166:167]
	global_load_dwordx4 v[174:177], v[128:129], off
	global_load_dwordx4 v[200:203], v[128:129], off offset:64
	global_load_dwordx4 v[204:207], v[128:129], off offset:512
	global_load_dwordx4 v[208:211], v[128:129], off offset:576
	v_or_b32_e32 v128, 16, v146
	v_ashrrev_i32_e32 v129, 31, v128
	v_lshlrev_b64 v[248:249], 13, v[128:129]
	v_lshl_add_u64 v[128:129], v[164:165], 0, v[248:249]
	global_load_dwordx4 v[212:215], v[128:129], off
	global_load_dwordx4 v[216:219], v[128:129], off offset:64
	global_load_dwordx4 v[220:223], v[128:129], off offset:512
	global_load_dwordx4 v[224:227], v[128:129], off offset:576
	v_or_b32_e32 v128, 32, v146
	v_ashrrev_i32_e32 v129, 31, v128
	v_lshlrev_b64 v[188:189], 13, v[128:129]
	v_lshl_add_u64 v[128:129], v[164:165], 0, v[188:189]
	global_load_dwordx4 v[228:231], v[128:129], off
	global_load_dwordx4 v[232:235], v[128:129], off offset:64
	global_load_dwordx4 v[236:239], v[128:129], off offset:512
	global_load_dwordx4 v[240:243], v[128:129], off offset:576
	v_or_b32_e32 v128, 48, v146
	v_ashrrev_i32_e32 v129, 31, v128
	v_lshlrev_b64 v[168:169], 13, v[128:129]
	v_lshl_add_u64 v[128:129], v[164:165], 0, v[168:169]
	global_load_dwordx4 v[244:247], v[128:129], off
	global_load_dwordx4 v[136:139], v[128:129], off offset:64
	global_load_dwordx4 v[132:135], v[128:129], off offset:512
	s_nop 0
	global_load_dwordx4 v[128:131], v[128:129], off offset:576
	v_lshl_add_u64 v[190:191], s[60:61], 0, v[166:167]
	v_lshl_add_u64 v[190:191], v[190:191], 0, v[162:163]
	v_lshl_add_u64 v[188:189], s[60:61], 0, v[188:189]
	v_lshl_add_u64 v[188:189], v[188:189], 0, v[162:163]
	v_lshl_add_u64 v[168:169], s[60:61], 0, v[168:169]
	v_lshl_add_u64 v[168:169], v[168:169], 0, v[162:163]
	s_mov_b64 s[16:17], 0x100000
	s_waitcnt vmcnt(0)
;     __device__ __forceinline__ void operator()(const f32x4 (&acc)[2][2][4][2], const Unit& u, int wr, int wc, int fr, int fq) const {
;     ...
;         for (int ai = 0; ai < 2; ++ai) {
;             f32x4 bs[4][2][2];
; #pragma unroll
;             for (int m = 0; m < 4; ++m) { const size_t off = (size_t)(row0 + ai * HALF + m * 16) * DM + col0;
; #pragma unroll
;                 for (int bj = 0; bj < 2; ++bj)
; #pragma unroll
;                     for (int n = 0; n < 2; ++n) bs[m][bj][n] = *(const f32x4*)(base + off + bj * HALF + n * 16); }
; #pragma unroll
;             for (int m = 0; m < 4; ++m) { const size_t off = (size_t)(row0 + ai * HALF + m * 16) * DM + col0;
; #pragma unroll
;                 for (int bj = 0; bj < 2; ++bj)
; #pragma unroll
;                     for (int n = 0; n < 2; ++n) *(f32x4*)(out + off + bj * HALF + n * 16) = bs[m][bj][n] + scale * acc[ai][bj][m][n]; }
	v_pk_fma_f32 v[176:177], v[126:127], 0.5, v[176:177] op_sel_hi:[1,0,1]
	v_pk_fma_f32 v[174:175], v[124:125], 0.5, v[174:175] op_sel_hi:[1,0,1]
	global_store_dwordx4 v[190:191], v[174:177], off
	v_pk_fma_f32 v[138:139], v[82:83], 0.5, v[138:139] op_sel_hi:[1,0,1]
	s_nop 0
	v_pk_fma_f32 v[176:177], v[122:123], 0.5, v[202:203] op_sel_hi:[1,0,1]
	v_pk_fma_f32 v[174:175], v[120:121], 0.5, v[200:201] op_sel_hi:[1,0,1]
	global_store_dwordx4 v[190:191], v[174:177], off offset:64
	v_pk_fma_f32 v[136:137], v[80:81], 0.5, v[136:137] op_sel_hi:[1,0,1]
	v_pk_fma_f32 v[134:135], v[70:71], 0.5, v[134:135] op_sel_hi:[1,0,1]
	v_pk_fma_f32 v[176:177], v[110:111], 0.5, v[206:207] op_sel_hi:[1,0,1]
	v_pk_fma_f32 v[174:175], v[108:109], 0.5, v[204:205] op_sel_hi:[1,0,1]
	global_store_dwordx4 v[190:191], v[174:177], off offset:512
	v_pk_fma_f32 v[132:133], v[68:69], 0.5, v[132:133] op_sel_hi:[1,0,1]
	v_pk_fma_f32 v[130:131], v[66:67], 0.5, v[130:131] op_sel_hi:[1,0,1]
	v_pk_fma_f32 v[176:177], v[106:107], 0.5, v[210:211] op_sel_hi:[1,0,1]
	v_pk_fma_f32 v[174:175], v[104:105], 0.5, v[208:209] op_sel_hi:[1,0,1]
	global_store_dwordx4 v[190:191], v[174:177], off offset:576
	v_lshl_add_u64 v[190:191], s[60:61], 0, v[248:249]
	v_lshl_add_u64 v[190:191], v[190:191], 0, v[162:163]
	v_pk_fma_f32 v[176:177], v[118:119], 0.5, v[214:215] op_sel_hi:[1,0,1]
	v_pk_fma_f32 v[174:175], v[116:117], 0.5, v[212:213] op_sel_hi:[1,0,1]
	global_store_dwordx4 v[190:191], v[174:177], off
	v_pk_fma_f32 v[128:129], v[64:65], 0.5, v[128:129] op_sel_hi:[1,0,1]
	global_store_dwordx4 v[168:169], v[136:139], off offset:64
	v_pk_fma_f32 v[176:177], v[114:115], 0.5, v[218:219] op_sel_hi:[1,0,1]
	v_pk_fma_f32 v[174:175], v[112:113], 0.5, v[216:217] op_sel_hi:[1,0,1]
	global_store_dwordx4 v[190:191], v[174:177], off offset:64
	global_store_dwordx4 v[168:169], v[132:135], off offset:512
	global_store_dwordx4 v[168:169], v[128:131], off offset:576
	v_pk_fma_f32 v[176:177], v[94:95], 0.5, v[222:223] op_sel_hi:[1,0,1]
	v_pk_fma_f32 v[174:175], v[92:93], 0.5, v[220:221] op_sel_hi:[1,0,1]
	global_store_dwordx4 v[190:191], v[174:177], off offset:512
	s_nop 1
	v_pk_fma_f32 v[176:177], v[90:91], 0.5, v[226:227] op_sel_hi:[1,0,1]
	v_pk_fma_f32 v[174:175], v[88:89], 0.5, v[224:225] op_sel_hi:[1,0,1]
	global_store_dwordx4 v[190:191], v[174:177], off offset:576
	s_nop 1
	v_pk_fma_f32 v[176:177], v[102:103], 0.5, v[230:231] op_sel_hi:[1,0,1]
	v_pk_fma_f32 v[174:175], v[100:101], 0.5, v[228:229] op_sel_hi:[1,0,1]
	global_store_dwordx4 v[188:189], v[174:177], off
	s_nop 1
	v_pk_fma_f32 v[176:177], v[98:99], 0.5, v[234:235] op_sel_hi:[1,0,1]
	v_pk_fma_f32 v[174:175], v[96:97], 0.5, v[232:233] op_sel_hi:[1,0,1]
	global_store_dwordx4 v[188:189], v[174:177], off offset:64
	s_nop 1
	v_pk_fma_f32 v[176:177], v[78:79], 0.5, v[238:239] op_sel_hi:[1,0,1]
	v_pk_fma_f32 v[174:175], v[76:77], 0.5, v[236:237] op_sel_hi:[1,0,1]
	global_store_dwordx4 v[188:189], v[174:177], off offset:512
	s_nop 1
	v_pk_fma_f32 v[176:177], v[74:75], 0.5, v[242:243] op_sel_hi:[1,0,1]
	v_pk_fma_f32 v[174:175], v[72:73], 0.5, v[240:241] op_sel_hi:[1,0,1]
	global_store_dwordx4 v[188:189], v[174:177], off offset:576
	s_nop 1
	v_pk_fma_f32 v[176:177], v[86:87], 0.5, v[246:247] op_sel_hi:[1,0,1]
	v_pk_fma_f32 v[174:175], v[84:85], 0.5, v[244:245] op_sel_hi:[1,0,1]
	global_store_dwordx4 v[168:169], v[174:177], off
	v_lshl_add_u64 v[168:169], v[166:167], 0, s[16:17]
	v_lshl_add_u64 v[128:129], v[164:165], 0, v[168:169]
	global_load_dwordx4 v[174:177], v[128:129], off
	global_load_dwordx4 v[200:203], v[128:129], off offset:64
	global_load_dwordx4 v[204:207], v[128:129], off offset:512
	global_load_dwordx4 v[208:211], v[128:129], off offset:576
	s_mov_b64 s[16:17], 0x120000
	v_lshl_add_u64 v[188:189], v[166:167], 0, s[16:17]
	v_lshl_add_u64 v[128:129], v[164:165], 0, v[188:189]
	global_load_dwordx4 v[212:215], v[128:129], off
	global_load_dwordx4 v[216:219], v[128:129], off offset:64
	global_load_dwordx4 v[220:223], v[128:129], off offset:512
	global_load_dwordx4 v[224:227], v[128:129], off offset:576
	s_mov_b64 s[16:17], 0x140000
	v_lshl_add_u64 v[190:191], v[166:167], 0, s[16:17]
	v_lshl_add_u64 v[128:129], v[164:165], 0, v[190:191]
	s_mov_b64 s[16:17], 0x160000
	global_load_dwordx4 v[228:231], v[128:129], off
	global_load_dwordx4 v[232:235], v[128:129], off offset:64
	global_load_dwordx4 v[236:239], v[128:129], off offset:512
	global_load_dwordx4 v[240:243], v[128:129], off offset:576
	v_lshl_add_u64 v[166:167], v[166:167], 0, s[16:17]
	v_lshl_add_u64 v[128:129], v[164:165], 0, v[166:167]
	global_load_dwordx4 v[244:247], v[128:129], off
	global_load_dwordx4 v[136:139], v[128:129], off offset:64
	global_load_dwordx4 v[132:135], v[128:129], off offset:512
	s_nop 0
	global_load_dwordx4 v[128:131], v[128:129], off offset:576
	v_lshl_add_u64 v[164:165], s[60:61], 0, v[168:169]
	v_lshl_add_u64 v[164:165], v[164:165], 0, v[162:163]
	s_mov_b64 s[16:17], 0
	s_waitcnt vmcnt(0)
;     __device__ __forceinline__ void operator()(const f32x4 (&acc)[2][2][4][2], const Unit& u, int wr, int wc, int fr, int fq) const {
;     ...
;             for (int m = 0; m < 4; ++m) { const size_t off = (size_t)(row0 + ai * HALF + m * 16) * DM + col0;
; #pragma unroll
;                 for (int bj = 0; bj < 2; ++bj)
; #pragma unroll
;                     for (int n = 0; n < 2; ++n) *(f32x4*)(out + off + bj * HALF + n * 16) = bs[m][bj][n] + scale * acc[ai][bj][m][n]; }
	v_pk_fma_f32 v[176:177], v[62:63], 0.5, v[176:177] op_sel_hi:[1,0,1]
	v_pk_fma_f32 v[174:175], v[60:61], 0.5, v[174:175] op_sel_hi:[1,0,1]
	global_store_dwordx4 v[164:165], v[174:177], off
	v_pk_fma_f32 v[138:139], v[18:19], 0.5, v[138:139] op_sel_hi:[1,0,1]
	s_nop 0
	v_pk_fma_f32 v[176:177], v[58:59], 0.5, v[202:203] op_sel_hi:[1,0,1]
	v_pk_fma_f32 v[174:175], v[56:57], 0.5, v[200:201] op_sel_hi:[1,0,1]
	global_store_dwordx4 v[164:165], v[174:177], off offset:64
	v_pk_fma_f32 v[136:137], v[16:17], 0.5, v[136:137] op_sel_hi:[1,0,1]
	v_pk_fma_f32 v[134:135], v[6:7], 0.5, v[134:135] op_sel_hi:[1,0,1]
	v_pk_fma_f32 v[176:177], v[46:47], 0.5, v[206:207] op_sel_hi:[1,0,1]
	v_pk_fma_f32 v[174:175], v[44:45], 0.5, v[204:205] op_sel_hi:[1,0,1]
	global_store_dwordx4 v[164:165], v[174:177], off offset:512
	v_pk_fma_f32 v[132:133], v[4:5], 0.5, v[132:133] op_sel_hi:[1,0,1]
	v_pk_fma_f32 v[130:131], v[2:3], 0.5, v[130:131] op_sel_hi:[1,0,1]
	v_pk_fma_f32 v[176:177], v[42:43], 0.5, v[210:211] op_sel_hi:[1,0,1]
	v_pk_fma_f32 v[174:175], v[40:41], 0.5, v[208:209] op_sel_hi:[1,0,1]
	global_store_dwordx4 v[164:165], v[174:177], off offset:576
	v_lshl_add_u64 v[164:165], s[60:61], 0, v[188:189]
	v_lshl_add_u64 v[164:165], v[164:165], 0, v[162:163]
	v_pk_fma_f32 v[176:177], v[54:55], 0.5, v[214:215] op_sel_hi:[1,0,1]
	v_pk_fma_f32 v[174:175], v[52:53], 0.5, v[212:213] op_sel_hi:[1,0,1]
	global_store_dwordx4 v[164:165], v[174:177], off
	v_pk_fma_f32 v[128:129], v[0:1], 0.5, v[128:129] op_sel_hi:[1,0,1]
	s_nop 0
	v_pk_fma_f32 v[176:177], v[50:51], 0.5, v[218:219] op_sel_hi:[1,0,1]
	v_pk_fma_f32 v[174:175], v[48:49], 0.5, v[216:217] op_sel_hi:[1,0,1]
	global_store_dwordx4 v[164:165], v[174:177], off offset:64
	s_nop 1
	v_pk_fma_f32 v[176:177], v[30:31], 0.5, v[222:223] op_sel_hi:[1,0,1]
	v_pk_fma_f32 v[174:175], v[28:29], 0.5, v[220:221] op_sel_hi:[1,0,1]
	global_store_dwordx4 v[164:165], v[174:177], off offset:512
	s_nop 1
	v_pk_fma_f32 v[176:177], v[26:27], 0.5, v[226:227] op_sel_hi:[1,0,1]
	v_pk_fma_f32 v[174:175], v[24:25], 0.5, v[224:225] op_sel_hi:[1,0,1]
	global_store_dwordx4 v[164:165], v[174:177], off offset:576
	v_lshl_add_u64 v[164:165], s[60:61], 0, v[190:191]
	v_lshl_add_u64 v[164:165], v[164:165], 0, v[162:163]
	v_pk_fma_f32 v[176:177], v[38:39], 0.5, v[230:231] op_sel_hi:[1,0,1]
	v_pk_fma_f32 v[174:175], v[36:37], 0.5, v[228:229] op_sel_hi:[1,0,1]
	global_store_dwordx4 v[164:165], v[174:177], off
	s_nop 1
	v_pk_fma_f32 v[176:177], v[34:35], 0.5, v[234:235] op_sel_hi:[1,0,1]
	v_pk_fma_f32 v[174:175], v[32:33], 0.5, v[232:233] op_sel_hi:[1,0,1]
	global_store_dwordx4 v[164:165], v[174:177], off offset:64
	s_nop 1
	v_pk_fma_f32 v[176:177], v[14:15], 0.5, v[238:239] op_sel_hi:[1,0,1]
	v_pk_fma_f32 v[174:175], v[12:13], 0.5, v[236:237] op_sel_hi:[1,0,1]
	global_store_dwordx4 v[164:165], v[174:177], off offset:512
	s_nop 1
	v_pk_fma_f32 v[176:177], v[10:11], 0.5, v[242:243] op_sel_hi:[1,0,1]
	v_pk_fma_f32 v[174:175], v[8:9], 0.5, v[240:241] op_sel_hi:[1,0,1]
	global_store_dwordx4 v[164:165], v[174:177], off offset:576
	v_lshl_add_u64 v[164:165], s[60:61], 0, v[166:167]
	v_lshl_add_u64 v[162:163], v[164:165], 0, v[162:163]
	v_pk_fma_f32 v[176:177], v[22:23], 0.5, v[246:247] op_sel_hi:[1,0,1]
	v_pk_fma_f32 v[174:175], v[20:21], 0.5, v[244:245] op_sel_hi:[1,0,1]
	global_store_dwordx4 v[162:163], v[174:177], off
	global_store_dwordx4 v[162:163], v[136:139], off offset:64
	global_store_dwordx4 v[162:163], v[132:135], off offset:512
	global_store_dwordx4 v[162:163], v[128:131], off offset:576

; #define PG8_STAGE(bufoff, gbase, voff) do { _Pragma("unroll") for (int _i = 0; _i < 2; ++_i) \
;         __builtin_amdgcn_global_load_lds((const unsigned*)((const char*)(gbase) + (voff)[_i]), (LAS unsigned*)(lds + (bufoff) + ldsw + _i * 8192), 16, 0, 0); } while (0)
; #define PG8_LDA(dst, b, h) do { _Pragma("unroll") for (int m = 0; m < 4; ++m) _Pragma("unroll") for (int k = 0; k < 2; ++k) dst[m][k] = *(const LAS bf16x8*)(lds + PG8_SA(b, h) + aoff + m * 2048 + k * 1024); } while (0)
; #define PG8_LDB(dst, b, h) do { _Pragma("unroll") for (int n = 0; n < 2; ++n) _Pragma("unroll") for (int k = 0; k < 2; ++k) dst[n][k] = *(const LAS bf16x8*)(lds + PG8_SB(b, h) + boff + n * 2048 + k * 1024); } while (0)
; #define PG8_MMA(ai, bj, At, Bt) do { __builtin_amdgcn_s_setprio(1); _Pragma("unroll") for (int m = 0; m < 4; ++m) _Pragma("unroll") for (int n = 0; n < 2; ++n) _Pragma("unroll") for (int k = 0; k < 2; ++k) \
;         acc[ai][bj][m][n] = __builtin_amdgcn_mfma_f32_16x16x32_bf16(Bt[n][k], At[m][k], acc[ai][bj][m][n], 0, 0, 0); __builtin_amdgcn_s_setprio(0); } while (0)
; #define PG8_WAIT_V(n) asm volatile("s_waitcnt vmcnt(" #n ")" ::: "memory")
; #define PG8_WAIT_L(n) asm volatile("s_waitcnt lgkmcnt(" #n ")" ::: "memory")
; template <class Epi, class Sched>
; __device__ __forceinline__ void gemm_phase(LAS unsigned char* lds, const Gemm g, const Sched& S, const Epi& E) {
;     ...
;         for (int t = 0; t < nt; t += 2) {
;             const bool last = (t == nt - 2);
;             const char* a1 = cA + (size_t)(t + 1) * kstep;
;             const char* a2 = last ? nA : cA + (size_t)(t + 2) * kstep; const char* b2 = last ? nB : cB + (size_t)(t + 2) * kstep;
;             const char* a3 = a2 + kstep; const char* b3 = b2 + kstep;
;             PG8_LDB(B0, 0, 0); PG8_SCHED; PG8_LDA(At, 0, 0); PG8_STAGE(PG8_SA(1, 1), a1 + hstep, voffA);
;             PG8_WAIT_L(8); PG8_BAR; PG8_WAIT_L(0); PG8_MMA(0, 0, At, B0); PG8_BAR; PG8_SCHED;
;             PG8_LDB(B1, 0, 1); PG8_STAGE(PG8_SB(0, 0), b2, voffB);
;             PG8_BAR; PG8_WAIT_L(0); PG8_MMA(0, 1, At, B1); PG8_BAR;
;             PG8_LDA(At, 0, 1); PG8_STAGE(PG8_SA(0, 0), a2, voffA);
;             PG8_BAR; PG8_WAIT_L(0); PG8_MMA(1, 0, At, B0); PG8_BAR; PG8_SCHED;
;             PG8_STAGE(PG8_SB(0, 1), b2 + hstep, voffB);
;             PG8_WAIT_V(6); PG8_BAR; PG8_MMA(1, 1, At, B1); PG8_BAR;
.LBB0_267:
	s_add_i32 s47, s22, 2
	s_add_u32 s20, s16, 0x100
	s_addc_u32 s21, s17, 0
	s_add_i32 s48, 0, 0x10000
	v_add_u32_e32 v140, s48, v201
	ds_read_b128 v[128:131], v140
	ds_read_b128 v[132:135], v140 offset:1024
	ds_read_b128 v[136:139], v140 offset:2048
	ds_read_b128 v[140:143], v140 offset:3072
	s_cmp_eq_u32 s11, s22
	s_cselect_b32 s22, s4, s13
	s_cselect_b32 s25, s7, s21
	s_cselect_b32 s24, s6, s20
	s_cselect_b32 s23, s5, s15
	s_add_i32 m0, s33, 0xc000
	ds_read_b128 v[144:147], v203
	ds_read_b128 v[166:169], v203 offset:1024
	ds_read_b128 v[170:173], v203 offset:2048
	ds_read_b128 v[174:177], v203 offset:3072
	ds_read_b128 v[204:207], v203 offset:4096
	ds_read_b128 v[208:211], v203 offset:5120
	ds_read_b128 v[212:215], v203 offset:6144
	ds_read_b128 v[216:219], v203 offset:7168
	global_load_lds_dwordx4 v162, s[16:17]
	s_add_i32 m0, s33, 0xe000
	s_nop 0
	global_load_lds_dwordx4 v164, s[16:17]
	s_waitcnt lgkmcnt(8)
	s_barrier
	s_waitcnt lgkmcnt(0)
	s_waitcnt lgkmcnt(0)
	v_mfma_f32_16x16x32_bf16 v[124:127], v[128:131], v[144:147], v[124:127]
	v_mfma_f32_16x16x32_bf16 v[120:123], v[136:139], v[144:147], v[120:123]
	v_mfma_f32_16x16x32_bf16 v[116:119], v[128:131], v[170:173], v[116:119]
	v_mfma_f32_16x16x32_bf16 v[112:115], v[136:139], v[170:173], v[112:115]
	v_mfma_f32_16x16x32_bf16 v[100:103], v[128:131], v[204:207], v[100:103]
	v_mfma_f32_16x16x32_bf16 v[96:99], v[136:139], v[204:207], v[96:99]
	v_mfma_f32_16x16x32_bf16 v[84:87], v[128:131], v[212:215], v[84:87]
	v_mfma_f32_16x16x32_bf16 v[80:83], v[136:139], v[212:215], v[80:83]
	v_mfma_f32_16x16x32_bf16 v[124:127], v[132:135], v[166:169], v[124:127]
	v_mfma_f32_16x16x32_bf16 v[120:123], v[140:143], v[166:169], v[120:123]
	v_mfma_f32_16x16x32_bf16 v[116:119], v[132:135], v[174:177], v[116:119]
	v_mfma_f32_16x16x32_bf16 v[112:115], v[140:143], v[174:177], v[112:115]
	v_mfma_f32_16x16x32_bf16 v[100:103], v[132:135], v[208:211], v[100:103]
	v_mfma_f32_16x16x32_bf16 v[96:99], v[140:143], v[208:211], v[96:99]
	v_mfma_f32_16x16x32_bf16 v[84:87], v[132:135], v[216:219], v[84:87]
	v_mfma_f32_16x16x32_bf16 v[80:83], v[140:143], v[216:219], v[80:83]
	s_barrier
	s_add_i32 s49, 0, 0x14000
	v_add_u32_e32 v188, s49, v201
	s_add_i32 s16, s48, s31
	ds_read_b128 v[220:223], v188
	ds_read_b128 v[224:227], v188 offset:1024
	ds_read_b128 v[228:231], v188 offset:2048
	ds_read_b128 v[232:235], v188 offset:3072
	s_add_u32 s84, s22, 0x80
	s_addc_u32 s85, s23, 0
	s_mov_b32 m0, s16
	s_nop 0
	global_load_lds_dwordx4 v148, s[22:23]
	s_add_i32 m0, s16, 0x2000
	s_nop 0
	global_load_lds_dwordx4 v160, s[22:23]
	s_barrier
	s_waitcnt lgkmcnt(0)
	s_waitcnt lgkmcnt(0)
	v_mfma_f32_16x16x32_bf16 v[108:111], v[220:223], v[144:147], v[108:111]
	v_mfma_f32_16x16x32_bf16 v[104:107], v[228:231], v[144:147], v[104:107]
	v_mfma_f32_16x16x32_bf16 v[92:95], v[220:223], v[170:173], v[92:95]
	v_mfma_f32_16x16x32_bf16 v[88:91], v[228:231], v[170:173], v[88:91]
	v_mfma_f32_16x16x32_bf16 v[76:79], v[220:223], v[204:207], v[76:79]
	v_mfma_f32_16x16x32_bf16 v[72:75], v[228:231], v[204:207], v[72:75]
	v_mfma_f32_16x16x32_bf16 v[68:71], v[220:223], v[212:215], v[68:71]
	v_mfma_f32_16x16x32_bf16 v[64:67], v[228:231], v[212:215], v[64:67]
	v_mfma_f32_16x16x32_bf16 v[108:111], v[224:227], v[166:169], v[108:111]
	v_mfma_f32_16x16x32_bf16 v[104:107], v[232:235], v[166:169], v[104:107]
	v_mfma_f32_16x16x32_bf16 v[92:95], v[224:227], v[174:177], v[92:95]
	v_mfma_f32_16x16x32_bf16 v[88:91], v[232:235], v[174:177], v[88:91]
	v_mfma_f32_16x16x32_bf16 v[76:79], v[224:227], v[208:211], v[76:79]
	v_mfma_f32_16x16x32_bf16 v[72:75], v[232:235], v[208:211], v[72:75]
	v_mfma_f32_16x16x32_bf16 v[68:71], v[224:227], v[216:219], v[68:71]
	v_mfma_f32_16x16x32_bf16 v[64:67], v[232:235], v[216:219], v[64:67]
	s_mov_b32 m0, s33
	s_add_u32 s86, s24, 0x80
	s_addc_u32 s87, s25, 0
	s_barrier
	ds_read_b128 v[144:147], v203 offset:16384
	ds_read_b128 v[166:169], v203 offset:17408
	ds_read_b128 v[170:173], v203 offset:18432
	ds_read_b128 v[174:177], v203 offset:19456
	ds_read_b128 v[204:207], v203 offset:20480
	ds_read_b128 v[208:211], v203 offset:21504
	ds_read_b128 v[212:215], v203 offset:22528
	ds_read_b128 v[216:219], v203 offset:23552
	global_load_lds_dwordx4 v148, s[24:25]
	s_mov_b32 m0, s34
	s_nop 0
	global_load_lds_dwordx4 v160, s[24:25]
	s_barrier
	s_waitcnt lgkmcnt(0)
	s_waitcnt lgkmcnt(0)
	v_mfma_f32_16x16x32_bf16 v[60:63], v[128:131], v[144:147], v[60:63]
	v_mfma_f32_16x16x32_bf16 v[56:59], v[136:139], v[144:147], v[56:59]
	v_mfma_f32_16x16x32_bf16 v[52:55], v[128:131], v[170:173], v[52:55]
	v_mfma_f32_16x16x32_bf16 v[48:51], v[136:139], v[170:173], v[48:51]
	v_mfma_f32_16x16x32_bf16 v[36:39], v[128:131], v[204:207], v[36:39]
	v_mfma_f32_16x16x32_bf16 v[32:35], v[136:139], v[204:207], v[32:35]
	v_mfma_f32_16x16x32_bf16 v[20:23], v[128:131], v[212:215], v[20:23]
	v_mfma_f32_16x16x32_bf16 v[16:19], v[136:139], v[212:215], v[16:19]
	v_mfma_f32_16x16x32_bf16 v[60:63], v[132:135], v[166:169], v[60:63]
	v_mfma_f32_16x16x32_bf16 v[56:59], v[140:143], v[166:169], v[56:59]
	v_mfma_f32_16x16x32_bf16 v[52:55], v[132:135], v[174:177], v[52:55]
	v_mfma_f32_16x16x32_bf16 v[48:51], v[140:143], v[174:177], v[48:51]
	v_mfma_f32_16x16x32_bf16 v[36:39], v[132:135], v[208:211], v[36:39]
	v_mfma_f32_16x16x32_bf16 v[32:35], v[140:143], v[208:211], v[32:35]
	v_mfma_f32_16x16x32_bf16 v[20:23], v[132:135], v[216:219], v[20:23]
	v_mfma_f32_16x16x32_bf16 v[16:19], v[140:143], v[216:219], v[16:19]
	s_barrier
	s_add_u32 s16, s22, 0x80000
	s_addc_u32 s17, s23, 0
	s_add_i32 s48, s49, s31
	s_mov_b32 m0, s48
	s_nop 0
	global_load_lds_dwordx4 v148, s[16:17]
	s_add_i32 m0, s48, 0x2000
	s_nop 0
	global_load_lds_dwordx4 v160, s[16:17]
	s_waitcnt vmcnt(6)
	s_barrier
; #define PG8_STAGE(bufoff, gbase, voff) do { _Pragma("unroll") for (int _i = 0; _i < 2; ++_i) \
;         __builtin_amdgcn_global_load_lds((const unsigned*)((const char*)(gbase) + (voff)[_i]), (LAS unsigned*)(lds + (bufoff) + ldsw + _i * 8192), 16, 0, 0); } while (0)
; #define PG8_LDA(dst, b, h) do { _Pragma("unroll") for (int m = 0; m < 4; ++m) _Pragma("unroll") for (int k = 0; k < 2; ++k) dst[m][k] = *(const LAS bf16x8*)(lds + PG8_SA(b, h) + aoff + m * 2048 + k * 1024); } while (0)
; #define PG8_LDB(dst, b, h) do { _Pragma("unroll") for (int n = 0; n < 2; ++n) _Pragma("unroll") for (int k = 0; k < 2; ++k) dst[n][k] = *(const LAS bf16x8*)(lds + PG8_SB(b, h) + boff + n * 2048 + k * 1024); } while (0)
; #define PG8_MMA(ai, bj, At, Bt) do { __builtin_amdgcn_s_setprio(1); _Pragma("unroll") for (int m = 0; m < 4; ++m) _Pragma("unroll") for (int n = 0; n < 2; ++n) _Pragma("unroll") for (int k = 0; k < 2; ++k) \
;         acc[ai][bj][m][n] = __builtin_amdgcn_mfma_f32_16x16x32_bf16(Bt[n][k], At[m][k], acc[ai][bj][m][n], 0, 0, 0); __builtin_amdgcn_s_setprio(0); } while (0)
; #define PG8_WAIT_L(n) asm volatile("s_waitcnt lgkmcnt(" #n ")" ::: "memory")
; #define PG8_BAR __builtin_amdgcn_s_barrier()
; #define PG8_SCHED __builtin_amdgcn_sched_barrier(0)
; template <class Epi, class Sched>
; __device__ __forceinline__ void gemm_phase(LAS unsigned char* lds, const Gemm g, const Sched& S, const Epi& E) {
;     ...
;             PG8_LDB(B0, 1, 0); PG8_SCHED; PG8_LDA(At, 1, 0); PG8_STAGE(PG8_SA(0, 1), a2 + hstep, voffA);
;             PG8_WAIT_L(8); PG8_BAR; PG8_WAIT_L(0); PG8_MMA(0, 0, At, B0); PG8_BAR; PG8_SCHED;
;             PG8_LDB(B1, 1, 1); PG8_STAGE(PG8_SB(1, 0), b3, voffB);
;             PG8_BAR; PG8_WAIT_L(0); PG8_MMA(0, 1, At, B1); PG8_BAR;
;             PG8_LDA(At, 1, 1); PG8_STAGE(PG8_SA(1, 0), a3, voffA);
;             PG8_BAR; PG8_WAIT_L(0); PG8_MMA(1, 0, At, B0); PG8_BAR; PG8_SCHED;
	v_mfma_f32_16x16x32_bf16 v[44:47], v[220:223], v[144:147], v[44:47]
	v_mfma_f32_16x16x32_bf16 v[40:43], v[228:231], v[144:147], v[40:43]
	v_mfma_f32_16x16x32_bf16 v[28:31], v[220:223], v[170:173], v[28:31]
	v_mfma_f32_16x16x32_bf16 v[24:27], v[228:231], v[170:173], v[24:27]
	v_mfma_f32_16x16x32_bf16 v[12:15], v[220:223], v[204:207], v[12:15]
	v_mfma_f32_16x16x32_bf16 v[8:11], v[228:231], v[204:207], v[8:11]
	v_mfma_f32_16x16x32_bf16 v[4:7], v[220:223], v[212:215], v[4:7]
	v_mfma_f32_16x16x32_bf16 v[0:3], v[228:231], v[212:215], v[0:3]
	v_mfma_f32_16x16x32_bf16 v[44:47], v[224:227], v[166:169], v[44:47]
	v_mfma_f32_16x16x32_bf16 v[40:43], v[232:235], v[166:169], v[40:43]
	v_mfma_f32_16x16x32_bf16 v[28:31], v[224:227], v[174:177], v[28:31]
	v_mfma_f32_16x16x32_bf16 v[24:27], v[232:235], v[174:177], v[24:27]
	v_mfma_f32_16x16x32_bf16 v[12:15], v[224:227], v[208:211], v[12:15]
	v_mfma_f32_16x16x32_bf16 v[8:11], v[232:235], v[208:211], v[8:11]
	v_mfma_f32_16x16x32_bf16 v[4:7], v[224:227], v[216:219], v[4:7]
	v_mfma_f32_16x16x32_bf16 v[0:3], v[232:235], v[216:219], v[0:3]
	s_add_i32 s48, 0, 0x18000
	v_add_u32_e32 v140, s48, v201
	s_barrier
	ds_read_b128 v[128:131], v140
	ds_read_b128 v[132:135], v140 offset:1024
	ds_read_b128 v[136:139], v140 offset:2048
	ds_read_b128 v[140:143], v140 offset:3072
	s_add_u32 s16, s24, 0x80000
	s_addc_u32 s17, s25, 0
	s_mov_b32 m0, s35
	ds_read_b128 v[144:147], v203 offset:32768
	ds_read_b128 v[166:169], v203 offset:33792
	ds_read_b128 v[170:173], v203 offset:34816
	ds_read_b128 v[174:177], v203 offset:35840
	ds_read_b128 v[204:207], v203 offset:36864
	ds_read_b128 v[208:211], v203 offset:37888
	ds_read_b128 v[212:215], v203 offset:38912
	ds_read_b128 v[216:219], v203 offset:39936
	global_load_lds_dwordx4 v148, s[16:17]
	s_mov_b32 m0, s36
	s_nop 0
	global_load_lds_dwordx4 v160, s[16:17]
	s_waitcnt lgkmcnt(8)
	s_barrier
	s_waitcnt lgkmcnt(0)
	s_waitcnt lgkmcnt(0)
	v_mfma_f32_16x16x32_bf16 v[124:127], v[128:131], v[144:147], v[124:127]
	v_mfma_f32_16x16x32_bf16 v[120:123], v[136:139], v[144:147], v[120:123]
	v_mfma_f32_16x16x32_bf16 v[116:119], v[128:131], v[170:173], v[116:119]
	v_mfma_f32_16x16x32_bf16 v[112:115], v[136:139], v[170:173], v[112:115]
	v_mfma_f32_16x16x32_bf16 v[100:103], v[128:131], v[204:207], v[100:103]
	v_mfma_f32_16x16x32_bf16 v[96:99], v[136:139], v[204:207], v[96:99]
	v_mfma_f32_16x16x32_bf16 v[84:87], v[128:131], v[212:215], v[84:87]
	v_mfma_f32_16x16x32_bf16 v[80:83], v[136:139], v[212:215], v[80:83]
	v_mfma_f32_16x16x32_bf16 v[124:127], v[132:135], v[166:169], v[124:127]
	v_mfma_f32_16x16x32_bf16 v[120:123], v[140:143], v[166:169], v[120:123]
	v_mfma_f32_16x16x32_bf16 v[116:119], v[132:135], v[174:177], v[116:119]
	v_mfma_f32_16x16x32_bf16 v[112:115], v[140:143], v[174:177], v[112:115]
	v_mfma_f32_16x16x32_bf16 v[100:103], v[132:135], v[208:211], v[100:103]
	v_mfma_f32_16x16x32_bf16 v[96:99], v[140:143], v[208:211], v[96:99]
	v_mfma_f32_16x16x32_bf16 v[84:87], v[132:135], v[216:219], v[84:87]
	v_mfma_f32_16x16x32_bf16 v[80:83], v[140:143], v[216:219], v[80:83]
	s_barrier
	s_add_i32 s24, 0, 0x1c000
	s_add_i32 s16, s48, s31
	v_add_u32_e32 v232, s24, v201
	s_mov_b32 m0, s16
	ds_read_b128 v[220:223], v232
	ds_read_b128 v[224:227], v232 offset:1024
	ds_read_b128 v[228:231], v232 offset:2048
	ds_read_b128 v[232:235], v232 offset:3072
	global_load_lds_dwordx4 v148, s[84:85]
	s_add_i32 m0, s16, 0x2000
	s_nop 0
	global_load_lds_dwordx4 v160, s[84:85]
	s_barrier
	s_waitcnt lgkmcnt(0)
	s_waitcnt lgkmcnt(0)
	v_mfma_f32_16x16x32_bf16 v[108:111], v[220:223], v[144:147], v[108:111]
	v_mfma_f32_16x16x32_bf16 v[104:107], v[228:231], v[144:147], v[104:107]
	v_mfma_f32_16x16x32_bf16 v[92:95], v[220:223], v[170:173], v[92:95]
	v_mfma_f32_16x16x32_bf16 v[88:91], v[228:231], v[170:173], v[88:91]
	v_mfma_f32_16x16x32_bf16 v[76:79], v[220:223], v[204:207], v[76:79]
	v_mfma_f32_16x16x32_bf16 v[72:75], v[228:231], v[204:207], v[72:75]
	v_mfma_f32_16x16x32_bf16 v[68:71], v[220:223], v[212:215], v[68:71]
	v_mfma_f32_16x16x32_bf16 v[64:67], v[228:231], v[212:215], v[64:67]
	v_mfma_f32_16x16x32_bf16 v[108:111], v[224:227], v[166:169], v[108:111]
	v_mfma_f32_16x16x32_bf16 v[104:107], v[232:235], v[166:169], v[104:107]
	v_mfma_f32_16x16x32_bf16 v[92:95], v[224:227], v[174:177], v[92:95]
	v_mfma_f32_16x16x32_bf16 v[88:91], v[232:235], v[174:177], v[88:91]
	v_mfma_f32_16x16x32_bf16 v[76:79], v[224:227], v[208:211], v[76:79]
	v_mfma_f32_16x16x32_bf16 v[72:75], v[232:235], v[208:211], v[72:75]
	v_mfma_f32_16x16x32_bf16 v[68:71], v[224:227], v[216:219], v[68:71]
	v_mfma_f32_16x16x32_bf16 v[64:67], v[232:235], v[216:219], v[64:67]
	s_mov_b32 m0, s39
	s_barrier
	ds_read_b128 v[144:147], v203 offset:49152
	ds_read_b128 v[166:169], v203 offset:50176
	ds_read_b128 v[170:173], v203 offset:51200
	ds_read_b128 v[174:177], v203 offset:52224
	ds_read_b128 v[204:207], v203 offset:53248
	ds_read_b128 v[208:211], v203 offset:54272
	ds_read_b128 v[212:215], v203 offset:55296
	ds_read_b128 v[216:219], v203 offset:56320
	global_load_lds_dwordx4 v148, s[86:87]
	s_mov_b32 m0, s40
	s_nop 0
	global_load_lds_dwordx4 v160, s[86:87]
	s_barrier
; #define PG8_STAGE(bufoff, gbase, voff) do { _Pragma("unroll") for (int _i = 0; _i < 2; ++_i) \
;         __builtin_amdgcn_global_load_lds((const unsigned*)((const char*)(gbase) + (voff)[_i]), (LAS unsigned*)(lds + (bufoff) + ldsw + _i * 8192), 16, 0, 0); } while (0)
; #define PG8_MMA(ai, bj, At, Bt) do { __builtin_amdgcn_s_setprio(1); _Pragma("unroll") for (int m = 0; m < 4; ++m) _Pragma("unroll") for (int n = 0; n < 2; ++n) _Pragma("unroll") for (int k = 0; k < 2; ++k) \
;         acc[ai][bj][m][n] = __builtin_amdgcn_mfma_f32_16x16x32_bf16(Bt[n][k], At[m][k], acc[ai][bj][m][n], 0, 0, 0); __builtin_amdgcn_s_setprio(0); } while (0)
; #define PG8_WAIT_V(n) asm volatile("s_waitcnt vmcnt(" #n ")" ::: "memory")
; #define PG8_BAR __builtin_amdgcn_s_barrier()
;     __device__ __forceinline__ void operator()(const f32x4 (&acc)[2][2][4][2], const Unit& u, int wr, int wc, int fr, int fq) const {
;     ...
;         for (int ai = 0; ai < 2; ++ai) {
;             f32x4 bs[4][2][2];
; #pragma unroll
;             for (int m = 0; m < 4; ++m) { const size_t off = (size_t)(row0 + ai * HALF + m * 16) * DM + col0;
; #pragma unroll
;                 for (int bj = 0; bj < 2; ++bj)
; #pragma unroll
;                     for (int n = 0; n < 2; ++n) bs[m][bj][n] = *(const f32x4*)(base + off + bj * HALF + n * 16); }
; template <class Epi, class Sched>
; __device__ __forceinline__ void gemm_phase(LAS unsigned char* lds, const Gemm g, const Sched& S, const Epi& E) {
;     ...
;             PG8_STAGE(PG8_SB(1, 1), b3 + hstep, voffB);
;             PG8_WAIT_V(6); PG8_BAR; PG8_MMA(1, 1, At, B1); PG8_BAR;
;         }
;         E(acc, cur, wr, wc, fr, fq);
;         if (!has_next) break;
	s_waitcnt lgkmcnt(0)
	s_waitcnt lgkmcnt(0)
	v_mfma_f32_16x16x32_bf16 v[60:63], v[128:131], v[144:147], v[60:63]
	v_mfma_f32_16x16x32_bf16 v[56:59], v[136:139], v[144:147], v[56:59]
	v_mfma_f32_16x16x32_bf16 v[52:55], v[128:131], v[170:173], v[52:55]
	v_mfma_f32_16x16x32_bf16 v[48:51], v[136:139], v[170:173], v[48:51]
	v_mfma_f32_16x16x32_bf16 v[36:39], v[128:131], v[204:207], v[36:39]
	v_mfma_f32_16x16x32_bf16 v[32:35], v[136:139], v[204:207], v[32:35]
	v_mfma_f32_16x16x32_bf16 v[20:23], v[128:131], v[212:215], v[20:23]
	v_mfma_f32_16x16x32_bf16 v[16:19], v[136:139], v[212:215], v[16:19]
	v_mfma_f32_16x16x32_bf16 v[60:63], v[132:135], v[166:169], v[60:63]
	v_mfma_f32_16x16x32_bf16 v[56:59], v[140:143], v[166:169], v[56:59]
	v_mfma_f32_16x16x32_bf16 v[52:55], v[132:135], v[174:177], v[52:55]
	v_mfma_f32_16x16x32_bf16 v[48:51], v[140:143], v[174:177], v[48:51]
	v_mfma_f32_16x16x32_bf16 v[36:39], v[132:135], v[208:211], v[36:39]
	v_mfma_f32_16x16x32_bf16 v[32:35], v[140:143], v[208:211], v[32:35]
	v_mfma_f32_16x16x32_bf16 v[20:23], v[132:135], v[216:219], v[20:23]
	v_mfma_f32_16x16x32_bf16 v[16:19], v[140:143], v[216:219], v[16:19]
	s_barrier
	s_add_u32 s16, s22, 0x80080
	s_addc_u32 s17, s23, 0
	s_add_i32 s22, s24, s31
	s_mov_b32 m0, s22
	s_nop 0
	global_load_lds_dwordx4 v148, s[16:17]
	s_add_i32 m0, s22, 0x2000
	s_nop 0
	global_load_lds_dwordx4 v160, s[16:17]
	s_waitcnt vmcnt(6)
	s_barrier
	v_mfma_f32_16x16x32_bf16 v[44:47], v[220:223], v[144:147], v[44:47]
	v_mfma_f32_16x16x32_bf16 v[40:43], v[228:231], v[144:147], v[40:43]
	v_mfma_f32_16x16x32_bf16 v[28:31], v[220:223], v[170:173], v[28:31]
	v_mfma_f32_16x16x32_bf16 v[24:27], v[228:231], v[170:173], v[24:27]
	v_mfma_f32_16x16x32_bf16 v[12:15], v[220:223], v[204:207], v[12:15]
	v_mfma_f32_16x16x32_bf16 v[8:11], v[228:231], v[204:207], v[8:11]
	v_mfma_f32_16x16x32_bf16 v[4:7], v[220:223], v[212:215], v[4:7]
	v_mfma_f32_16x16x32_bf16 v[0:3], v[228:231], v[212:215], v[0:3]
	v_mfma_f32_16x16x32_bf16 v[44:47], v[224:227], v[166:169], v[44:47]
	v_mfma_f32_16x16x32_bf16 v[40:43], v[232:235], v[166:169], v[40:43]
	v_mfma_f32_16x16x32_bf16 v[28:31], v[224:227], v[174:177], v[28:31]
	v_mfma_f32_16x16x32_bf16 v[24:27], v[232:235], v[174:177], v[24:27]
	v_mfma_f32_16x16x32_bf16 v[12:15], v[224:227], v[208:211], v[12:15]
	v_mfma_f32_16x16x32_bf16 v[8:11], v[232:235], v[208:211], v[8:11]
	v_mfma_f32_16x16x32_bf16 v[4:7], v[224:227], v[216:219], v[4:7]
	v_mfma_f32_16x16x32_bf16 v[0:3], v[232:235], v[216:219], v[0:3]
	s_add_u32 s13, s13, 0x100
	s_addc_u32 s15, s15, 0
	s_cmp_ge_i32 s47, s45
	s_mov_b64 s[16:17], s[20:21]
	s_mov_b32 s22, s47
	s_barrier
	s_cbranch_scc0 .LBB0_267
	v_lshl_add_u32 v166, s46, 8, v200
	v_lshl_or_b32 v168, s44, 8, v202
	s_mov_b64 s[16:17], -1
	s_cmp_lt_i32 s82, 0
	v_ashrrev_i32_e32 v169, 31, v168
	v_ashrrev_i32_e32 v167, 31, v166
	s_cbranch_scc0 .LBB0_270
	v_lshlrev_b64 v[170:171], 2, v[168:169]
	v_lshl_add_u64 v[172:173], s[60:61], 0, v[170:171]
	v_lshlrev_b64 v[174:175], 13, v[166:167]
	v_lshl_add_u64 v[128:129], v[172:173], 0, v[174:175]
	global_load_dwordx4 v[204:207], v[128:129], off
	global_load_dwordx4 v[208:211], v[128:129], off offset:64
	global_load_dwordx4 v[212:215], v[128:129], off offset:512
	global_load_dwordx4 v[216:219], v[128:129], off offset:576
	v_or_b32_e32 v128, 16, v166
	v_ashrrev_i32_e32 v129, 31, v128
	v_lshlrev_b64 v[188:189], 13, v[128:129]
	v_lshl_add_u64 v[128:129], v[172:173], 0, v[188:189]
	global_load_dwordx4 v[220:223], v[128:129], off
	global_load_dwordx4 v[224:227], v[128:129], off offset:64
	global_load_dwordx4 v[228:231], v[128:129], off offset:512
	global_load_dwordx4 v[232:235], v[128:129], off offset:576
	v_or_b32_e32 v128, 32, v166
	v_ashrrev_i32_e32 v129, 31, v128
	v_lshlrev_b64 v[190:191], 13, v[128:129]
	v_lshl_add_u64 v[128:129], v[172:173], 0, v[190:191]
	global_load_dwordx4 v[236:239], v[128:129], off
	global_load_dwordx4 v[240:243], v[128:129], off offset:64
	global_load_dwordx4 v[144:147], v[128:129], off offset:512
	global_load_dwordx4 v[140:143], v[128:129], off offset:576
	v_or_b32_e32 v128, 48, v166
	v_ashrrev_i32_e32 v129, 31, v128
	v_lshlrev_b64 v[176:177], 13, v[128:129]
	v_lshl_add_u64 v[128:129], v[172:173], 0, v[176:177]
	global_load_dwordx4 v[244:247], v[128:129], off
	global_load_dwordx4 v[136:139], v[128:129], off offset:64
	global_load_dwordx4 v[132:135], v[128:129], off offset:512
	s_nop 0
	global_load_dwordx4 v[128:131], v[128:129], off offset:576
	v_lshl_add_u64 v[248:249], s[60:61], 0, v[174:175]
	v_lshl_add_u64 v[248:249], v[248:249], 0, v[170:171]
	v_lshl_add_u64 v[188:189], s[60:61], 0, v[188:189]
	v_lshl_add_u64 v[188:189], v[188:189], 0, v[170:171]
	s_mov_b64 s[16:17], 0x100000
	s_waitcnt vmcnt(0)
;     __device__ __forceinline__ void operator()(const f32x4 (&acc)[2][2][4][2], const Unit& u, int wr, int wc, int fr, int fq) const {
;     ...
;         for (int ai = 0; ai < 2; ++ai) {
;             f32x4 bs[4][2][2];
; #pragma unroll
;             for (int m = 0; m < 4; ++m) { const size_t off = (size_t)(row0 + ai * HALF + m * 16) * DM + col0;
; #pragma unroll
;                 for (int bj = 0; bj < 2; ++bj)
; #pragma unroll
;                     for (int n = 0; n < 2; ++n) bs[m][bj][n] = *(const f32x4*)(base + off + bj * HALF + n * 16); }
; #pragma unroll
;             for (int m = 0; m < 4; ++m) { const size_t off = (size_t)(row0 + ai * HALF + m * 16) * DM + col0;
; #pragma unroll
;                 for (int bj = 0; bj < 2; ++bj)
; #pragma unroll
;                     for (int n = 0; n < 2; ++n) *(f32x4*)(out + off + bj * HALF + n * 16) = bs[m][bj][n] + scale * acc[ai][bj][m][n]; }
	v_pk_add_f32 v[206:207], v[206:207], v[126:127]
	v_pk_add_f32 v[204:205], v[204:205], v[124:125]
	global_store_dwordx4 v[248:249], v[204:207], off
	v_pk_add_f32 v[146:147], v[146:147], v[78:79]
	s_nop 0
	v_pk_add_f32 v[206:207], v[210:211], v[122:123]
	v_pk_add_f32 v[204:205], v[208:209], v[120:121]
	global_store_dwordx4 v[248:249], v[204:207], off offset:64
	v_pk_add_f32 v[144:145], v[144:145], v[76:77]
	v_pk_add_f32 v[142:143], v[142:143], v[74:75]
	v_pk_add_f32 v[206:207], v[214:215], v[110:111]
	v_pk_add_f32 v[204:205], v[212:213], v[108:109]
	global_store_dwordx4 v[248:249], v[204:207], off offset:512
	v_pk_add_f32 v[140:141], v[140:141], v[72:73]
	v_pk_add_f32 v[138:139], v[138:139], v[82:83]
	v_pk_add_f32 v[206:207], v[218:219], v[106:107]
	v_pk_add_f32 v[204:205], v[216:217], v[104:105]
	global_store_dwordx4 v[248:249], v[204:207], off offset:576
	v_pk_add_f32 v[136:137], v[136:137], v[80:81]
	v_pk_add_f32 v[134:135], v[134:135], v[70:71]
	v_pk_add_f32 v[206:207], v[222:223], v[118:119]
	v_pk_add_f32 v[204:205], v[220:221], v[116:117]
	global_store_dwordx4 v[188:189], v[204:207], off
	v_pk_add_f32 v[132:133], v[132:133], v[68:69]
	v_pk_add_f32 v[130:131], v[130:131], v[66:67]
	v_pk_add_f32 v[206:207], v[226:227], v[114:115]
	v_pk_add_f32 v[204:205], v[224:225], v[112:113]
	global_store_dwordx4 v[188:189], v[204:207], off offset:64
	v_pk_add_f32 v[128:129], v[128:129], v[64:65]
	s_nop 0
	v_pk_add_f32 v[206:207], v[230:231], v[94:95]
	v_pk_add_f32 v[204:205], v[228:229], v[92:93]
	global_store_dwordx4 v[188:189], v[204:207], off offset:512
	s_nop 1
	v_pk_add_f32 v[206:207], v[234:235], v[90:91]
	v_pk_add_f32 v[204:205], v[232:233], v[88:89]
	global_store_dwordx4 v[188:189], v[204:207], off offset:576
	v_lshl_add_u64 v[188:189], s[60:61], 0, v[190:191]
	v_lshl_add_u64 v[188:189], v[188:189], 0, v[170:171]
	v_pk_add_f32 v[206:207], v[238:239], v[102:103]
	v_pk_add_f32 v[204:205], v[236:237], v[100:101]
	global_store_dwordx4 v[188:189], v[144:147], off offset:512
	global_store_dwordx4 v[188:189], v[204:207], off
	global_store_dwordx4 v[188:189], v[140:143], off offset:576
	v_lshl_add_u64 v[144:145], s[60:61], 0, v[176:177]
	v_pk_add_f32 v[206:207], v[242:243], v[98:99]
	v_pk_add_f32 v[204:205], v[240:241], v[96:97]
	v_pk_add_f32 v[142:143], v[246:247], v[86:87]
	v_pk_add_f32 v[140:141], v[244:245], v[84:85]
	v_lshl_add_u64 v[144:145], v[144:145], 0, v[170:171]
	global_store_dwordx4 v[188:189], v[204:207], off offset:64
	global_store_dwordx4 v[144:145], v[140:143], off
	global_store_dwordx4 v[144:145], v[136:139], off offset:64
	global_store_dwordx4 v[144:145], v[132:135], off offset:512
	global_store_dwordx4 v[144:145], v[128:131], off offset:576
	v_lshl_add_u64 v[146:147], v[174:175], 0, s[16:17]
	s_mov_b64 s[16:17], 0x120000
	v_lshl_add_u64 v[128:129], v[172:173], 0, v[146:147]
	global_load_dwordx4 v[142:145], v[128:129], off
	global_load_dwordx4 v[204:207], v[128:129], off offset:64
	global_load_dwordx4 v[208:211], v[128:129], off offset:512
	global_load_dwordx4 v[212:215], v[128:129], off offset:576
	v_lshl_add_u64 v[176:177], v[174:175], 0, s[16:17]
	v_lshl_add_u64 v[128:129], v[172:173], 0, v[176:177]
	global_load_dwordx4 v[216:219], v[128:129], off
	global_load_dwordx4 v[220:223], v[128:129], off offset:64
	global_load_dwordx4 v[224:227], v[128:129], off offset:512
	global_load_dwordx4 v[228:231], v[128:129], off offset:576
	s_mov_b64 s[16:17], 0x140000
	v_lshl_add_u64 v[188:189], v[174:175], 0, s[16:17]
	s_mov_b64 s[16:17], 0x160000
	v_lshl_add_u64 v[128:129], v[172:173], 0, v[188:189]
	v_lshl_add_u64 v[140:141], v[174:175], 0, s[16:17]
	global_load_dwordx4 v[232:235], v[128:129], off
	global_load_dwordx4 v[236:239], v[128:129], off offset:64
	global_load_dwordx4 v[240:243], v[128:129], off offset:512
	global_load_dwordx4 v[244:247], v[128:129], off offset:576
	v_lshl_add_u64 v[128:129], v[172:173], 0, v[140:141]
	global_load_dwordx4 v[172:175], v[128:129], off
	global_load_dwordx4 v[136:139], v[128:129], off offset:64
	global_load_dwordx4 v[132:135], v[128:129], off offset:512
	s_nop 0
	global_load_dwordx4 v[128:131], v[128:129], off offset:576
	v_lshl_add_u64 v[146:147], s[60:61], 0, v[146:147]
	v_lshl_add_u64 v[146:147], v[146:147], 0, v[170:171]
	v_lshl_add_u64 v[140:141], s[60:61], 0, v[140:141]
	v_lshl_add_u64 v[140:141], v[140:141], 0, v[170:171]
	s_mov_b64 s[16:17], 0
	s_waitcnt vmcnt(0)
;     __device__ __forceinline__ void operator()(const f32x4 (&acc)[2][2][4][2], const Unit& u, int wr, int wc, int fr, int fq) const {
;     ...
;             for (int m = 0; m < 4; ++m) { const size_t off = (size_t)(row0 + ai * HALF + m * 16) * DM + col0;
; #pragma unroll
;                 for (int bj = 0; bj < 2; ++bj)
; #pragma unroll
;                     for (int n = 0; n < 2; ++n) *(f32x4*)(out + off + bj * HALF + n * 16) = bs[m][bj][n] + scale * acc[ai][bj][m][n]; }
	v_pk_add_f32 v[144:145], v[62:63], v[144:145]
	v_pk_add_f32 v[142:143], v[60:61], v[142:143]
	global_store_dwordx4 v[146:147], v[142:145], off
	v_pk_add_f32 v[138:139], v[18:19], v[138:139]
	s_nop 0
	v_pk_add_f32 v[144:145], v[58:59], v[206:207]
	v_pk_add_f32 v[142:143], v[56:57], v[204:205]
	global_store_dwordx4 v[146:147], v[142:145], off offset:64
	v_pk_add_f32 v[136:137], v[16:17], v[136:137]
	v_pk_add_f32 v[134:135], v[6:7], v[134:135]
	v_pk_add_f32 v[144:145], v[46:47], v[210:211]
	v_pk_add_f32 v[142:143], v[44:45], v[208:209]
	global_store_dwordx4 v[146:147], v[142:145], off offset:512
	v_pk_add_f32 v[132:133], v[4:5], v[132:133]
	v_pk_add_f32 v[130:131], v[2:3], v[130:131]
	v_pk_add_f32 v[144:145], v[42:43], v[214:215]
	v_pk_add_f32 v[142:143], v[40:41], v[212:213]
	global_store_dwordx4 v[146:147], v[142:145], off offset:576
	v_lshl_add_u64 v[146:147], s[60:61], 0, v[176:177]
	v_lshl_add_u64 v[146:147], v[146:147], 0, v[170:171]
	v_pk_add_f32 v[144:145], v[54:55], v[218:219]
	v_pk_add_f32 v[142:143], v[52:53], v[216:217]
	global_store_dwordx4 v[146:147], v[142:145], off
	v_pk_add_f32 v[128:129], v[0:1], v[128:129]
	global_store_dwordx4 v[140:141], v[136:139], off offset:64
	v_pk_add_f32 v[144:145], v[50:51], v[222:223]
	v_pk_add_f32 v[142:143], v[48:49], v[220:221]
	global_store_dwordx4 v[146:147], v[142:145], off offset:64
	global_store_dwordx4 v[140:141], v[132:135], off offset:512
	global_store_dwordx4 v[140:141], v[128:131], off offset:576
	v_pk_add_f32 v[144:145], v[30:31], v[226:227]
	v_pk_add_f32 v[142:143], v[28:29], v[224:225]
	global_store_dwordx4 v[146:147], v[142:145], off offset:512
	s_nop 1
	v_pk_add_f32 v[144:145], v[26:27], v[230:231]
	v_pk_add_f32 v[142:143], v[24:25], v[228:229]
	global_store_dwordx4 v[146:147], v[142:145], off offset:576
	v_lshl_add_u64 v[146:147], s[60:61], 0, v[188:189]
	v_lshl_add_u64 v[146:147], v[146:147], 0, v[170:171]
	v_pk_add_f32 v[144:145], v[38:39], v[234:235]
	v_pk_add_f32 v[142:143], v[36:37], v[232:233]
	global_store_dwordx4 v[146:147], v[142:145], off
	s_nop 1
	v_pk_add_f32 v[144:145], v[34:35], v[238:239]
	v_pk_add_f32 v[142:143], v[32:33], v[236:237]
	global_store_dwordx4 v[146:147], v[142:145], off offset:64
	s_nop 1
	v_pk_add_f32 v[144:145], v[14:15], v[242:243]
	v_pk_add_f32 v[142:143], v[12:13], v[240:241]
	global_store_dwordx4 v[146:147], v[142:145], off offset:512
	s_nop 1
	v_pk_add_f32 v[144:145], v[10:11], v[246:247]
	v_pk_add_f32 v[142:143], v[8:9], v[244:245]
	global_store_dwordx4 v[146:147], v[142:145], off offset:576
	s_nop 1
	v_pk_add_f32 v[144:145], v[22:23], v[174:175]
	v_pk_add_f32 v[142:143], v[20:21], v[172:173]
	global_store_dwordx4 v[140:141], v[142:145], off
